# GEMM K-loops: template per-cluster s_setprio flips removed, one static s_setprio 1 for waves 0-3 during the K-loop
# speedup vs baseline: 1.0046x; 1.0046x over previous
; #define PG8_STAGE(bufoff, gbase, voff) do { _Pragma("unroll") for (int _i = 0; _i < 2; ++_i) \
;         __builtin_amdgcn_global_load_lds((const unsigned*)((const char*)(gbase) + (voff)[_i]), (PG8_LAS unsigned*)(lds + (bufoff) + ldsw + _i * 8192), 16, 0, 0); } while (0)
; #define PG8_LDA(dst, b, h) do { _Pragma("unroll") for (int m = 0; m < 4; ++m) _Pragma("unroll") for (int k = 0; k < 2; ++k) dst[m][k] = *(const PG8_LAS bf16x8*)(lds + PG8_SA(b, h) + aoff + m * 2048 + k * 1024); } while (0)
; #define PG8_LDB(dst, b, h) do { _Pragma("unroll") for (int n = 0; n < 2; ++n) _Pragma("unroll") for (int k = 0; k < 2; ++k) dst[n][k] = *(const PG8_LAS bf16x8*)(lds + PG8_SB(b, h) + boff + n * 2048 + k * 1024); } while (0)
; #define PG8_MMA(ai, bj, At, Bt) do { __builtin_amdgcn_s_setprio(1); _Pragma("unroll") for (int m = 0; m < 4; ++m) _Pragma("unroll") for (int n = 0; n < 2; ++n) _Pragma("unroll") for (int k = 0; k < 2; ++k) \
;         acc[ai][bj][m][n] = __builtin_amdgcn_mfma_f32_16x16x32_bf16(Bt[n][k], At[m][k], acc[ai][bj][m][n], 0, 0, 0); __builtin_amdgcn_s_setprio(0); } while (0)
; #define PG8_WAIT_V(n) asm volatile("s_waitcnt vmcnt(" #n ")" ::: "memory")
; #define PG8_WAIT_L(n) asm volatile("s_waitcnt lgkmcnt(" #n ")" ::: "memory")
; #define PG8_BAR __builtin_amdgcn_s_barrier()
; #define PG8_SCHED __builtin_amdgcn_sched_barrier(0)
; template <class Epi, class Sched, bool ALIGN_EPI = false, bool SP2 = false>
; __device__ __forceinline__ void gemm_phase(PG8_LAS unsigned char* lds, const Gemm g, const Sched& S, const Epi& E) {
;     ...
;             if constexpr (SP2) {
;             PG8_LDB(B0, 0, 0); PG8_LDB(B1, 0, 1); PG8_SCHED; PG8_LDA(At, 0, 0); PG8_STAGE(PG8_SA(1, 1), a1 + hstep, voffA);
;             PG8_WAIT_V(8); PG8_WAIT_L(0); PG8_BAR; PG8_MMA(0, 0, At, B0); PG8_MMA(0, 1, At, B1); PG8_BAR; PG8_SCHED;
.LBB0_606:
	s_ashr_i32 s23, s22, 31
	s_lshl_b64 s[24:25], s[22:23], 19
	s_add_u32 s24, s8, s24
	s_addc_u32 s25, s9, s25
	s_and_b64 s[26:27], s[2:3], exec
	s_cselect_b32 s23, s25, s29
	s_cselect_b32 s33, s24, s28
	s_ashr_i32 s21, s20, 31
	s_lshl_b64 s[26:27], s[20:21], 19
	s_add_u32 s26, s42, s26
	s_addc_u32 s27, s43, s27
	s_and_b64 s[34:35], s[2:3], exec
	s_cselect_b32 s21, s27, s31
	s_cselect_b32 s56, s26, s30
	s_add_u32 s28, s28, 0x40080
	s_addc_u32 s29, s29, 0
	s_add_u32 s57, s30, 0x100
	s_addc_u32 s58, s31, 0
	s_mov_b32 s59, -2
	v_mov_b64_e32 v[4:5], 0
	v_mov_b64_e32 v[6:7], 0
	v_mov_b64_e32 v[8:9], 0
	v_mov_b64_e32 v[10:11], 0
	v_mov_b64_e32 v[12:13], 0
	v_mov_b64_e32 v[14:15], 0
	v_mov_b64_e32 v[16:17], 0
	v_mov_b64_e32 v[18:19], 0
	v_mov_b64_e32 v[20:21], 0
	v_mov_b64_e32 v[22:23], 0
	v_mov_b64_e32 v[24:25], 0
	v_mov_b64_e32 v[26:27], 0
	v_mov_b64_e32 v[28:29], 0
	v_mov_b64_e32 v[30:31], 0
	v_mov_b64_e32 v[32:33], 0
	v_mov_b64_e32 v[34:35], 0
	v_mov_b64_e32 v[36:37], 0
	v_mov_b64_e32 v[38:39], 0
	v_mov_b64_e32 v[40:41], 0
	v_mov_b64_e32 v[42:43], 0
	v_mov_b64_e32 v[44:45], 0
	v_mov_b64_e32 v[46:47], 0
	v_mov_b64_e32 v[48:49], 0
	v_mov_b64_e32 v[50:51], 0
	v_mov_b64_e32 v[52:53], 0
	v_mov_b64_e32 v[54:55], 0
	v_mov_b64_e32 v[56:57], 0
	v_mov_b64_e32 v[58:59], 0
	v_mov_b64_e32 v[60:61], 0
	v_mov_b64_e32 v[62:63], 0
	v_mov_b64_e32 v[64:65], 0
	v_mov_b64_e32 v[66:67], 0
	v_mov_b64_e32 v[68:69], 0
	v_mov_b64_e32 v[70:71], 0
	v_mov_b64_e32 v[72:73], 0
	v_mov_b64_e32 v[74:75], 0
	v_mov_b64_e32 v[76:77], 0
	v_mov_b64_e32 v[78:79], 0
	v_mov_b64_e32 v[80:81], 0
	v_mov_b64_e32 v[82:83], 0
	v_mov_b64_e32 v[84:85], 0
	v_mov_b64_e32 v[86:87], 0
	v_mov_b64_e32 v[88:89], 0
	v_mov_b64_e32 v[90:91], 0
	v_mov_b64_e32 v[92:93], 0
	v_mov_b64_e32 v[94:95], 0
	v_mov_b64_e32 v[96:97], 0
	v_mov_b64_e32 v[98:99], 0
	v_mov_b64_e32 v[100:101], 0
	v_mov_b64_e32 v[102:103], 0
	v_mov_b64_e32 v[104:105], 0
	v_mov_b64_e32 v[106:107], 0
	v_mov_b64_e32 v[108:109], 0
	v_mov_b64_e32 v[110:111], 0
	v_mov_b64_e32 v[112:113], 0
	v_mov_b64_e32 v[114:115], 0
	v_mov_b64_e32 v[116:117], 0
	v_mov_b64_e32 v[118:119], 0
	v_mov_b64_e32 v[120:121], 0
	v_mov_b64_e32 v[122:123], 0
	v_mov_b64_e32 v[124:125], 0
	v_mov_b64_e32 v[126:127], 0
	v_mov_b64_e32 v[128:129], 0
	v_mov_b64_e32 v[130:131], 0
	v_readfirstlane_b32 s89, v0
	s_nop 3
	s_lshr_b32 s89, s89, 6
	s_cmp_lt_u32 s89, 4
	s_cbranch_scc0 .Lprio_done0
	s_setprio 1
.Lprio_done0:
.LBB0_607:
	s_add_u32 s30, s28, 0xfffc0080
	s_addc_u32 s31, s29, -1
	s_add_i32 s60, 0, 0x10000
	s_cmp_eq_u32 s59, 12
	s_cselect_b32 s35, s23, s31
	s_cselect_b32 s34, s33, s30
	v_add_u32_e32 v146, s60, v148
	s_cselect_b32 s31, s21, s58
	s_cselect_b32 s30, s56, s57
	s_add_i32 s62, 0, 0x14000
	ds_read_b128 v[142:145], v146
	ds_read_b128 v[152:155], v146 offset:1024
	ds_read_b128 v[156:159], v146 offset:2048
	ds_read_b128 v[160:163], v146 offset:3072
	v_add_u32_e32 v146, s62, v148
	ds_read_b128 v[164:167], v146
	ds_read_b128 v[168:171], v146 offset:1024
	ds_read_b128 v[172:175], v146 offset:2048
	ds_read_b128 v[176:179], v146 offset:3072
	v_lshl_add_u64 v[192:193], s[28:29], 0, v[138:139]
	s_add_i32 m0, s45, 0xc000
	ds_read_b128 v[180:183], v150
	ds_read_b128 v[184:187], v150 offset:1024
	ds_read_b128 v[188:191], v150 offset:2048
	ds_read_b128 v[204:207], v150 offset:3072
	ds_read_b128 v[220:223], v150 offset:4096
	ds_read_b128 v[224:227], v150 offset:5120
	ds_read_b128 v[228:231], v150 offset:6144
	ds_read_b128 v[232:235], v150 offset:7168
	global_load_lds_dwordx4 v[192:193], off
	v_lshl_add_u64 v[192:193], s[28:29], 0, v[140:141]
	s_add_i32 m0, s45, 0xe000
	s_nop 0
	global_load_lds_dwordx4 v[192:193], off
	s_waitcnt vmcnt(8)
	s_waitcnt lgkmcnt(0)
	s_barrier
	s_waitcnt lgkmcnt(0)
	v_mfma_f32_16x16x32_bf16 v[128:131], v[142:145], v[180:183], v[128:131]
	v_mfma_f32_16x16x32_bf16 v[120:123], v[156:159], v[180:183], v[120:123]
	v_mfma_f32_16x16x32_bf16 v[112:115], v[142:145], v[188:191], v[112:115]
	v_mfma_f32_16x16x32_bf16 v[104:107], v[156:159], v[188:191], v[104:107]
	v_mfma_f32_16x16x32_bf16 v[96:99], v[142:145], v[220:223], v[96:99]
	v_mfma_f32_16x16x32_bf16 v[88:91], v[156:159], v[220:223], v[88:91]
	v_mfma_f32_16x16x32_bf16 v[80:83], v[142:145], v[228:231], v[80:83]
	v_mfma_f32_16x16x32_bf16 v[72:75], v[156:159], v[228:231], v[72:75]
	v_mfma_f32_16x16x32_bf16 v[128:131], v[152:155], v[184:187], v[128:131]
	v_mfma_f32_16x16x32_bf16 v[120:123], v[160:163], v[184:187], v[120:123]
	v_mfma_f32_16x16x32_bf16 v[112:115], v[152:155], v[204:207], v[112:115]
	v_mfma_f32_16x16x32_bf16 v[104:107], v[160:163], v[204:207], v[104:107]
	v_mfma_f32_16x16x32_bf16 v[96:99], v[152:155], v[224:227], v[96:99]
	v_mfma_f32_16x16x32_bf16 v[88:91], v[160:163], v[224:227], v[88:91]
	v_mfma_f32_16x16x32_bf16 v[80:83], v[152:155], v[232:235], v[80:83]
	v_mfma_f32_16x16x32_bf16 v[72:75], v[160:163], v[232:235], v[72:75]
	v_mfma_f32_16x16x32_bf16 v[124:127], v[164:167], v[180:183], v[124:127]
	v_mfma_f32_16x16x32_bf16 v[116:119], v[172:175], v[180:183], v[116:119]
	v_mfma_f32_16x16x32_bf16 v[108:111], v[164:167], v[188:191], v[108:111]
	v_mfma_f32_16x16x32_bf16 v[100:103], v[172:175], v[188:191], v[100:103]
	v_mfma_f32_16x16x32_bf16 v[92:95], v[164:167], v[220:223], v[92:95]
	v_mfma_f32_16x16x32_bf16 v[84:87], v[172:175], v[220:223], v[84:87]
	v_mfma_f32_16x16x32_bf16 v[76:79], v[164:167], v[228:231], v[76:79]
	v_mfma_f32_16x16x32_bf16 v[68:71], v[172:175], v[228:231], v[68:71]
	v_mfma_f32_16x16x32_bf16 v[124:127], v[168:171], v[184:187], v[124:127]
	v_mfma_f32_16x16x32_bf16 v[116:119], v[176:179], v[184:187], v[116:119]
	v_mfma_f32_16x16x32_bf16 v[108:111], v[168:171], v[204:207], v[108:111]
	v_mfma_f32_16x16x32_bf16 v[100:103], v[176:179], v[204:207], v[100:103]
	v_mfma_f32_16x16x32_bf16 v[92:95], v[168:171], v[224:227], v[92:95]
	v_mfma_f32_16x16x32_bf16 v[84:87], v[176:179], v[224:227], v[84:87]
	v_mfma_f32_16x16x32_bf16 v[76:79], v[168:171], v[232:235], v[76:79]
	v_mfma_f32_16x16x32_bf16 v[68:71], v[176:179], v[232:235], v[68:71]
	s_barrier
; #define PG8_STAGE(bufoff, gbase, voff) do { _Pragma("unroll") for (int _i = 0; _i < 2; ++_i) \
;         __builtin_amdgcn_global_load_lds((const unsigned*)((const char*)(gbase) + (voff)[_i]), (PG8_LAS unsigned*)(lds + (bufoff) + ldsw + _i * 8192), 16, 0, 0); } while (0)
; #define PG8_LDA(dst, b, h) do { _Pragma("unroll") for (int m = 0; m < 4; ++m) _Pragma("unroll") for (int k = 0; k < 2; ++k) dst[m][k] = *(const PG8_LAS bf16x8*)(lds + PG8_SA(b, h) + aoff + m * 2048 + k * 1024); } while (0)
; #define PG8_LDB(dst, b, h) do { _Pragma("unroll") for (int n = 0; n < 2; ++n) _Pragma("unroll") for (int k = 0; k < 2; ++k) dst[n][k] = *(const PG8_LAS bf16x8*)(lds + PG8_SB(b, h) + boff + n * 2048 + k * 1024); } while (0)
; #define PG8_MMA(ai, bj, At, Bt) do { __builtin_amdgcn_s_setprio(1); _Pragma("unroll") for (int m = 0; m < 4; ++m) _Pragma("unroll") for (int n = 0; n < 2; ++n) _Pragma("unroll") for (int k = 0; k < 2; ++k) \
;         acc[ai][bj][m][n] = __builtin_amdgcn_mfma_f32_16x16x32_bf16(Bt[n][k], At[m][k], acc[ai][bj][m][n], 0, 0, 0); __builtin_amdgcn_s_setprio(0); } while (0)
; #define PG8_WAIT_V(n) asm volatile("s_waitcnt vmcnt(" #n ")" ::: "memory")
; #define PG8_WAIT_L(n) asm volatile("s_waitcnt lgkmcnt(" #n ")" ::: "memory")
; #define PG8_BAR __builtin_amdgcn_s_barrier()
; #define PG8_SCHED __builtin_amdgcn_sched_barrier(0)
; template <class Epi, class Sched, bool ALIGN_EPI = false, bool SP2 = false>
; __device__ __forceinline__ void gemm_phase(PG8_LAS unsigned char* lds, const Gemm g, const Sched& S, const Epi& E) {
;     ...
;             PG8_LDA(At, 0, 1); PG8_STAGE(PG8_SB(0, 0), b2, voffB); PG8_STAGE(PG8_SB(0, 1), b2 + hstep, voffB); PG8_STAGE(PG8_SA(0, 0), a2, voffA);
;             PG8_WAIT_V(8); PG8_WAIT_L(0); PG8_BAR; PG8_MMA(1, 0, At, B0); PG8_MMA(1, 1, At, B1); PG8_BAR; PG8_SCHED;
;             PG8_LDB(B0, 1, 0); PG8_LDB(B1, 1, 1); PG8_SCHED; PG8_LDA(At, 1, 0); PG8_STAGE(PG8_SA(0, 1), a2 + hstep, voffA);
;             PG8_WAIT_V(8); PG8_WAIT_L(0); PG8_BAR; PG8_MMA(0, 0, At, B0); PG8_MMA(0, 1, At, B1); PG8_BAR; PG8_SCHED;
	s_add_i32 s60, s60, s44
	v_lshl_add_u64 v[192:193], s[30:31], 0, v[2:3]
	s_mov_b32 m0, s60
	ds_read_b128 v[180:183], v150 offset:16384
	ds_read_b128 v[184:187], v150 offset:17408
	ds_read_b128 v[188:191], v150 offset:18432
	ds_read_b128 v[204:207], v150 offset:19456
	ds_read_b128 v[220:223], v150 offset:20480
	ds_read_b128 v[224:227], v150 offset:21504
	ds_read_b128 v[228:231], v150 offset:22528
	ds_read_b128 v[232:235], v150 offset:23552
	global_load_lds_dwordx4 v[192:193], off
	s_add_i32 m0, s60, 0x2000
	s_add_u32 s60, s30, 0x40000
	v_lshl_add_u64 v[194:195], s[30:31], 0, v[132:133]
	s_addc_u32 s61, s31, 0
	s_add_i32 s62, s62, s44
	global_load_lds_dwordx4 v[194:195], off
	v_lshl_add_u64 v[196:197], s[60:61], 0, v[2:3]
	s_mov_b32 m0, s62
	v_lshl_add_u64 v[236:237], s[34:35], 0, v[134:135]
	global_load_lds_dwordx4 v[196:197], off
	v_lshl_add_u64 v[196:197], s[60:61], 0, v[132:133]
	s_add_i32 m0, s62, 0x2000
	s_nop 0
	global_load_lds_dwordx4 v[196:197], off
	v_lshl_add_u64 v[196:197], s[34:35], 0, v[136:137]
	s_mov_b32 m0, s45
	s_nop 0
	global_load_lds_dwordx4 v[196:197], off
	s_mov_b32 m0, s46
	s_nop 0
	global_load_lds_dwordx4 v[236:237], off
	s_waitcnt vmcnt(8)
	s_waitcnt lgkmcnt(0)
	s_barrier
	s_waitcnt lgkmcnt(0)
	v_mfma_f32_16x16x32_bf16 v[64:67], v[142:145], v[180:183], v[64:67]
	v_mfma_f32_16x16x32_bf16 v[56:59], v[156:159], v[180:183], v[56:59]
	v_mfma_f32_16x16x32_bf16 v[48:51], v[142:145], v[188:191], v[48:51]
	v_mfma_f32_16x16x32_bf16 v[40:43], v[156:159], v[188:191], v[40:43]
	v_mfma_f32_16x16x32_bf16 v[32:35], v[142:145], v[220:223], v[32:35]
	v_mfma_f32_16x16x32_bf16 v[24:27], v[156:159], v[220:223], v[24:27]
	v_mfma_f32_16x16x32_bf16 v[16:19], v[142:145], v[228:231], v[16:19]
	v_mfma_f32_16x16x32_bf16 v[8:11], v[156:159], v[228:231], v[8:11]
	v_mfma_f32_16x16x32_bf16 v[64:67], v[152:155], v[184:187], v[64:67]
	v_mfma_f32_16x16x32_bf16 v[56:59], v[160:163], v[184:187], v[56:59]
	v_mfma_f32_16x16x32_bf16 v[48:51], v[152:155], v[204:207], v[48:51]
	v_mfma_f32_16x16x32_bf16 v[40:43], v[160:163], v[204:207], v[40:43]
	v_mfma_f32_16x16x32_bf16 v[32:35], v[152:155], v[224:227], v[32:35]
	v_mfma_f32_16x16x32_bf16 v[24:27], v[160:163], v[224:227], v[24:27]
	v_mfma_f32_16x16x32_bf16 v[16:19], v[152:155], v[232:235], v[16:19]
	v_mfma_f32_16x16x32_bf16 v[8:11], v[160:163], v[232:235], v[8:11]
	v_mfma_f32_16x16x32_bf16 v[60:63], v[164:167], v[180:183], v[60:63]
	v_mfma_f32_16x16x32_bf16 v[52:55], v[172:175], v[180:183], v[52:55]
	v_mfma_f32_16x16x32_bf16 v[44:47], v[164:167], v[188:191], v[44:47]
	v_mfma_f32_16x16x32_bf16 v[36:39], v[172:175], v[188:191], v[36:39]
	v_mfma_f32_16x16x32_bf16 v[28:31], v[164:167], v[220:223], v[28:31]
	v_mfma_f32_16x16x32_bf16 v[20:23], v[172:175], v[220:223], v[20:23]
	v_mfma_f32_16x16x32_bf16 v[12:15], v[164:167], v[228:231], v[12:15]
	v_mfma_f32_16x16x32_bf16 v[4:7], v[172:175], v[228:231], v[4:7]
	v_mfma_f32_16x16x32_bf16 v[60:63], v[168:171], v[184:187], v[60:63]
	v_mfma_f32_16x16x32_bf16 v[52:55], v[176:179], v[184:187], v[52:55]
	v_mfma_f32_16x16x32_bf16 v[44:47], v[168:171], v[204:207], v[44:47]
	v_mfma_f32_16x16x32_bf16 v[36:39], v[176:179], v[204:207], v[36:39]
	v_mfma_f32_16x16x32_bf16 v[28:31], v[168:171], v[224:227], v[28:31]
	v_mfma_f32_16x16x32_bf16 v[20:23], v[176:179], v[224:227], v[20:23]
	v_mfma_f32_16x16x32_bf16 v[12:15], v[168:171], v[232:235], v[12:15]
	v_mfma_f32_16x16x32_bf16 v[4:7], v[176:179], v[232:235], v[4:7]
	s_barrier
	s_add_i32 s60, 0, 0x18000
	v_add_u32_e32 v146, s60, v148
	s_add_i32 s61, 0, 0x1c000
	ds_read_b128 v[142:145], v146
	ds_read_b128 v[152:155], v146 offset:1024
	ds_read_b128 v[156:159], v146 offset:2048
	ds_read_b128 v[160:163], v146 offset:3072
	v_add_u32_e32 v146, s61, v148
	ds_read_b128 v[164:167], v146
	ds_read_b128 v[168:171], v146 offset:1024
	ds_read_b128 v[172:175], v146 offset:2048
	ds_read_b128 v[176:179], v146 offset:3072
	s_add_u32 s34, s34, 0x40000
	s_addc_u32 s35, s35, 0
	s_mov_b32 m0, s47
	v_lshl_add_u64 v[238:239], s[34:35], 0, v[136:137]
	ds_read_b128 v[180:183], v150 offset:32768
	ds_read_b128 v[184:187], v150 offset:33792
	ds_read_b128 v[188:191], v150 offset:34816
	ds_read_b128 v[204:207], v150 offset:35840
	ds_read_b128 v[220:223], v150 offset:36864
	ds_read_b128 v[224:227], v150 offset:37888
	ds_read_b128 v[228:231], v150 offset:38912
	ds_read_b128 v[232:235], v150 offset:39936
	global_load_lds_dwordx4 v[238:239], off
	v_lshl_add_u64 v[238:239], s[34:35], 0, v[134:135]
	s_mov_b32 m0, s50
	s_nop 0
	global_load_lds_dwordx4 v[238:239], off
	s_waitcnt vmcnt(8)
	s_waitcnt lgkmcnt(0)
	s_barrier
; #define PG8_STAGE(bufoff, gbase, voff) do { _Pragma("unroll") for (int _i = 0; _i < 2; ++_i) \
;         __builtin_amdgcn_global_load_lds((const unsigned*)((const char*)(gbase) + (voff)[_i]), (PG8_LAS unsigned*)(lds + (bufoff) + ldsw + _i * 8192), 16, 0, 0); } while (0)
; #define PG8_LDA(dst, b, h) do { _Pragma("unroll") for (int m = 0; m < 4; ++m) _Pragma("unroll") for (int k = 0; k < 2; ++k) dst[m][k] = *(const PG8_LAS bf16x8*)(lds + PG8_SA(b, h) + aoff + m * 2048 + k * 1024); } while (0)
; #define PG8_MMA(ai, bj, At, Bt) do { __builtin_amdgcn_s_setprio(1); _Pragma("unroll") for (int m = 0; m < 4; ++m) _Pragma("unroll") for (int n = 0; n < 2; ++n) _Pragma("unroll") for (int k = 0; k < 2; ++k) \
;         acc[ai][bj][m][n] = __builtin_amdgcn_mfma_f32_16x16x32_bf16(Bt[n][k], At[m][k], acc[ai][bj][m][n], 0, 0, 0); __builtin_amdgcn_s_setprio(0); } while (0)
; #define PG8_WAIT_V(n) asm volatile("s_waitcnt vmcnt(" #n ")" ::: "memory")
; #define PG8_WAIT_L(n) asm volatile("s_waitcnt lgkmcnt(" #n ")" ::: "memory")
; #define PG8_BAR __builtin_amdgcn_s_barrier()
; #define PG8_SCHED __builtin_amdgcn_sched_barrier(0)
; template <class Epi, class Sched, bool ALIGN_EPI = false, bool SP2 = false>
; __device__ __forceinline__ void gemm_phase(PG8_LAS unsigned char* lds, const Gemm g, const Sched& S, const Epi& E) {
;     ...
;             PG8_WAIT_V(8); PG8_WAIT_L(0); PG8_BAR; PG8_MMA(0, 0, At, B0); PG8_MMA(0, 1, At, B1); PG8_BAR; PG8_SCHED;
;             PG8_LDA(At, 1, 1); PG8_STAGE(PG8_SB(1, 0), b3, voffB); PG8_STAGE(PG8_SB(1, 1), b3 + hstep, voffB); PG8_STAGE(PG8_SA(1, 0), a3, voffA);
;             PG8_WAIT_V(8); PG8_WAIT_L(0); PG8_BAR; PG8_MMA(1, 0, At, B0); PG8_MMA(1, 1, At, B1); PG8_BAR; PG8_SCHED;
;     ...
;         if constexpr (ALIGN_EPI) { if (wr == 0) PG8_BAR; }
	s_waitcnt lgkmcnt(0)
	v_mfma_f32_16x16x32_bf16 v[128:131], v[142:145], v[180:183], v[128:131]
	v_mfma_f32_16x16x32_bf16 v[120:123], v[156:159], v[180:183], v[120:123]
	v_mfma_f32_16x16x32_bf16 v[112:115], v[142:145], v[188:191], v[112:115]
	v_mfma_f32_16x16x32_bf16 v[104:107], v[156:159], v[188:191], v[104:107]
	v_mfma_f32_16x16x32_bf16 v[96:99], v[142:145], v[220:223], v[96:99]
	v_mfma_f32_16x16x32_bf16 v[88:91], v[156:159], v[220:223], v[88:91]
	v_mfma_f32_16x16x32_bf16 v[80:83], v[142:145], v[228:231], v[80:83]
	v_mfma_f32_16x16x32_bf16 v[72:75], v[156:159], v[228:231], v[72:75]
	v_mfma_f32_16x16x32_bf16 v[128:131], v[152:155], v[184:187], v[128:131]
	v_mfma_f32_16x16x32_bf16 v[120:123], v[160:163], v[184:187], v[120:123]
	v_mfma_f32_16x16x32_bf16 v[112:115], v[152:155], v[204:207], v[112:115]
	v_mfma_f32_16x16x32_bf16 v[104:107], v[160:163], v[204:207], v[104:107]
	v_mfma_f32_16x16x32_bf16 v[96:99], v[152:155], v[224:227], v[96:99]
	v_mfma_f32_16x16x32_bf16 v[88:91], v[160:163], v[224:227], v[88:91]
	v_mfma_f32_16x16x32_bf16 v[80:83], v[152:155], v[232:235], v[80:83]
	v_mfma_f32_16x16x32_bf16 v[72:75], v[160:163], v[232:235], v[72:75]
	v_mfma_f32_16x16x32_bf16 v[124:127], v[164:167], v[180:183], v[124:127]
	v_mfma_f32_16x16x32_bf16 v[116:119], v[172:175], v[180:183], v[116:119]
	v_mfma_f32_16x16x32_bf16 v[108:111], v[164:167], v[188:191], v[108:111]
	v_mfma_f32_16x16x32_bf16 v[100:103], v[172:175], v[188:191], v[100:103]
	v_mfma_f32_16x16x32_bf16 v[92:95], v[164:167], v[220:223], v[92:95]
	v_mfma_f32_16x16x32_bf16 v[84:87], v[172:175], v[220:223], v[84:87]
	v_mfma_f32_16x16x32_bf16 v[76:79], v[164:167], v[228:231], v[76:79]
	v_mfma_f32_16x16x32_bf16 v[68:71], v[172:175], v[228:231], v[68:71]
	v_mfma_f32_16x16x32_bf16 v[124:127], v[168:171], v[184:187], v[124:127]
	v_mfma_f32_16x16x32_bf16 v[116:119], v[176:179], v[184:187], v[116:119]
	v_mfma_f32_16x16x32_bf16 v[108:111], v[168:171], v[204:207], v[108:111]
	v_mfma_f32_16x16x32_bf16 v[100:103], v[176:179], v[204:207], v[100:103]
	v_mfma_f32_16x16x32_bf16 v[92:95], v[168:171], v[224:227], v[92:95]
	v_mfma_f32_16x16x32_bf16 v[84:87], v[176:179], v[224:227], v[84:87]
	v_mfma_f32_16x16x32_bf16 v[76:79], v[168:171], v[232:235], v[76:79]
	v_mfma_f32_16x16x32_bf16 v[68:71], v[176:179], v[232:235], v[68:71]
	s_barrier
	s_add_i32 s34, s60, s44
	v_lshl_add_u64 v[192:193], v[192:193], 0, s[92:93]
	s_mov_b32 m0, s34
	ds_read_b128 v[180:183], v150 offset:49152
	ds_read_b128 v[184:187], v150 offset:50176
	ds_read_b128 v[188:191], v150 offset:51200
	ds_read_b128 v[204:207], v150 offset:52224
	ds_read_b128 v[220:223], v150 offset:53248
	ds_read_b128 v[224:227], v150 offset:54272
	ds_read_b128 v[228:231], v150 offset:55296
	ds_read_b128 v[232:235], v150 offset:56320
	global_load_lds_dwordx4 v[192:193], off
	s_add_i32 m0, s34, 0x2000
	s_add_u32 s30, s30, 0x40080
	v_lshl_add_u64 v[192:193], v[194:195], 0, s[92:93]
	s_addc_u32 s31, s31, 0
	s_add_i32 s34, s61, s44
	global_load_lds_dwordx4 v[192:193], off
	v_lshl_add_u64 v[192:193], s[30:31], 0, v[2:3]
	s_mov_b32 m0, s34
	s_nop 0
	global_load_lds_dwordx4 v[192:193], off
	v_lshl_add_u64 v[192:193], s[30:31], 0, v[132:133]
	s_add_i32 m0, s34, 0x2000
	s_nop 0
	global_load_lds_dwordx4 v[192:193], off
	v_lshl_add_u64 v[192:193], v[196:197], 0, s[92:93]
	s_mov_b32 m0, s51
	s_nop 0
	global_load_lds_dwordx4 v[192:193], off
	v_lshl_add_u64 v[192:193], v[236:237], 0, s[92:93]
	s_mov_b32 m0, s52
	s_nop 0
	global_load_lds_dwordx4 v[192:193], off
	s_waitcnt vmcnt(8)
	s_waitcnt lgkmcnt(0)
	s_barrier
	s_waitcnt lgkmcnt(0)
	v_mfma_f32_16x16x32_bf16 v[64:67], v[142:145], v[180:183], v[64:67]
	v_mfma_f32_16x16x32_bf16 v[56:59], v[156:159], v[180:183], v[56:59]
	v_mfma_f32_16x16x32_bf16 v[48:51], v[142:145], v[188:191], v[48:51]
	v_mfma_f32_16x16x32_bf16 v[40:43], v[156:159], v[188:191], v[40:43]
	v_mfma_f32_16x16x32_bf16 v[32:35], v[142:145], v[220:223], v[32:35]
	v_mfma_f32_16x16x32_bf16 v[24:27], v[156:159], v[220:223], v[24:27]
	v_mfma_f32_16x16x32_bf16 v[16:19], v[142:145], v[228:231], v[16:19]
	v_mfma_f32_16x16x32_bf16 v[8:11], v[156:159], v[228:231], v[8:11]
	v_mfma_f32_16x16x32_bf16 v[64:67], v[152:155], v[184:187], v[64:67]
	v_mfma_f32_16x16x32_bf16 v[56:59], v[160:163], v[184:187], v[56:59]
	v_mfma_f32_16x16x32_bf16 v[48:51], v[152:155], v[204:207], v[48:51]
	v_mfma_f32_16x16x32_bf16 v[40:43], v[160:163], v[204:207], v[40:43]
	v_mfma_f32_16x16x32_bf16 v[32:35], v[152:155], v[224:227], v[32:35]
	v_mfma_f32_16x16x32_bf16 v[24:27], v[160:163], v[224:227], v[24:27]
	v_mfma_f32_16x16x32_bf16 v[16:19], v[152:155], v[232:235], v[16:19]
	v_mfma_f32_16x16x32_bf16 v[8:11], v[160:163], v[232:235], v[8:11]
	v_mfma_f32_16x16x32_bf16 v[60:63], v[164:167], v[180:183], v[60:63]
	v_mfma_f32_16x16x32_bf16 v[52:55], v[172:175], v[180:183], v[52:55]
	v_mfma_f32_16x16x32_bf16 v[44:47], v[164:167], v[188:191], v[44:47]
	v_mfma_f32_16x16x32_bf16 v[36:39], v[172:175], v[188:191], v[36:39]
	v_mfma_f32_16x16x32_bf16 v[28:31], v[164:167], v[220:223], v[28:31]
	v_mfma_f32_16x16x32_bf16 v[20:23], v[172:175], v[220:223], v[20:23]
	v_mfma_f32_16x16x32_bf16 v[12:15], v[164:167], v[228:231], v[12:15]
	v_mfma_f32_16x16x32_bf16 v[4:7], v[172:175], v[228:231], v[4:7]
	v_mfma_f32_16x16x32_bf16 v[60:63], v[168:171], v[184:187], v[60:63]
	v_mfma_f32_16x16x32_bf16 v[52:55], v[176:179], v[184:187], v[52:55]
	v_mfma_f32_16x16x32_bf16 v[44:47], v[168:171], v[204:207], v[44:47]
	v_mfma_f32_16x16x32_bf16 v[36:39], v[176:179], v[204:207], v[36:39]
	v_mfma_f32_16x16x32_bf16 v[28:31], v[168:171], v[224:227], v[28:31]
	v_mfma_f32_16x16x32_bf16 v[20:23], v[176:179], v[224:227], v[20:23]
	v_mfma_f32_16x16x32_bf16 v[12:15], v[168:171], v[232:235], v[12:15]
	v_mfma_f32_16x16x32_bf16 v[4:7], v[176:179], v[232:235], v[4:7]
	s_barrier
	s_add_i32 s59, s59, 2
	s_add_u32 s28, s28, 0x100
	s_addc_u32 s29, s29, 0
	s_add_u32 s57, s57, 0x100
	s_addc_u32 s58, s58, 0
	s_cmp_gt_u32 s59, 13
	s_cbranch_scc0 .LBB0_607
	s_and_b64 vcc, exec, s[18:19]
	s_cbranch_vccz .LBB0_610
	s_barrier
; __device__ __forceinline__ unsigned cvt_pk_bf16(float lo, float hi) { unsigned r; asm volatile("v_cvt_pk_bf16_f32 %0, %1, %2" : "=v"(r) : "v"(lo), "v"(hi)); return r; }
;     __device__ __forceinline__ void operator()(const f32x4 (&acc)[2][2][4][2], const Unit& u, int wr, int wc, int fr, int fq) const {
;     ...
;             for (int m = 0; m < 4; ++m) { const int row = row0 + ai * HALF + m * 16; const f32x4 q0 = *(const f32x4*)(ssq + (size_t)row * 16), q1 = *(const f32x4*)(ssq + (size_t)row * 16 + 4), q2 = *(const f32x4*)(ssq + (size_t)row * 16 + 8), q3 = *(const f32x4*)(ssq + (size_t)row * 16 + 12);
;                 const float rs = rsqrtf(((((q0[0] + q0[1]) + (q0[2] + q0[3])) + ((q1[0] + q1[1]) + (q1[2] + q1[3]))) + (((q2[0] + q2[1]) + (q2[2] + q2[3])) + ((q3[0] + q3[1]) + (q3[2] + q3[3])))) * (1.0f / 1024.0f) + 1e-6f);
;                 float a[8];
; #pragma unroll
;                 for (int n = 0; n < 2; ++n)
; #pragma unroll
;                     for (int j = 0; j < 4; ++j) { const float g = acc[ai][0][m][n][j] * rs, up = acc[ai][1][m][n][j] * rs; a[4 * n + j] = g * up * __builtin_amdgcn_rcpf(1.0f + __expf(-g)); }
;                 u32x4 w; w.x = cvt_pk_bf16(a[0], a[1]); w.y = cvt_pk_bf16(a[2], a[3]); w.z = cvt_pk_bf16(a[4], a[5]); w.w = cvt_pk_bf16(a[6], a[7]);
;                 *(u32x4*)(O + (size_t)row * ldc + col0) = w; }
.LBB0_610:
	s_setprio 0
	v_readlane_b32 s28, v253, 45
	v_readlane_b32 s29, v253, 46
	v_lshl_add_u32 v192, s55, 8, v147
	v_and_b32_e32 v193, 24, v149
	v_lshlrev_b32_e32 v193, 1, v193
	v_lshl_add_u32 v193, v192, 6, v193
	v_add_u32_e32 v230, 0x2000, v193
	global_load_dwordx4 v[152:155], v193, s[16:17]
	global_load_dwordx4 v[156:159], v193, s[16:17] offset:1024
	global_load_dwordx4 v[160:163], v193, s[16:17] offset:2048
	global_load_dwordx4 v[164:167], v193, s[16:17] offset:3072
	global_load_dwordx4 v[168:171], v230, s[16:17]
	global_load_dwordx4 v[172:175], v230, s[16:17] offset:1024
	global_load_dwordx4 v[176:179], v230, s[16:17] offset:2048
	global_load_dwordx4 v[180:183], v230, s[16:17] offset:3072
	v_xor_b32_e32 v228, 16, v214
	v_lshlrev_b32_e32 v228, 2, v228
	v_xor_b32_e32 v229, 32, v214
	v_lshlrev_b32_e32 v229, 2, v229
	s_movk_i32 s21, 0x1600
	v_lshl_or_b32 v231, s54, 7, v149
	v_lshlrev_b32_e32 v231, 1, v231
	v_mad_u32_u24 v184, v192, s21, v231
	v_add_u32_e32 v185, 0x16000, v184
	v_add_u32_e32 v186, 0x16000, v185
	v_add_u32_e32 v187, 0x16000, v186
	v_add_u32_e32 v188, 0xb0000, v184
	v_add_u32_e32 v189, 0xb0000, v185
	v_add_u32_e32 v190, 0xb0000, v186
	v_add_u32_e32 v191, 0xb0000, v187
	s_waitcnt vmcnt(7)
	v_add_f32_e32 v154, v154, v155
	v_add_f32_e32 v194, v152, v153
	v_add_f32_e32 v194, v194, v154
	s_waitcnt vmcnt(6)
	v_add_f32_e32 v158, v158, v159
	v_add_f32_e32 v195, v156, v157
	v_add_f32_e32 v195, v195, v158
	s_waitcnt vmcnt(5)
	v_add_f32_e32 v162, v162, v163
	v_add_f32_e32 v196, v160, v161
	v_add_f32_e32 v196, v196, v162
	s_waitcnt vmcnt(4)
	v_add_f32_e32 v166, v166, v167
	v_add_f32_e32 v197, v164, v165
	v_add_f32_e32 v197, v197, v166
	s_waitcnt vmcnt(3)
	v_add_f32_e32 v170, v170, v171
	v_add_f32_e32 v204, v168, v169
	v_add_f32_e32 v204, v204, v170
	s_waitcnt vmcnt(2)
	v_add_f32_e32 v174, v174, v175
	v_add_f32_e32 v205, v172, v173
	v_add_f32_e32 v205, v205, v174
	s_waitcnt vmcnt(1)
	v_add_f32_e32 v178, v178, v179
	v_add_f32_e32 v206, v176, v177
	v_add_f32_e32 v206, v206, v178
	s_waitcnt vmcnt(0)
	v_add_f32_e32 v182, v182, v183
	v_add_f32_e32 v207, v180, v181
	v_add_f32_e32 v207, v207, v182
	ds_bpermute_b32 v220, v228, v194
	ds_bpermute_b32 v221, v228, v195
	ds_bpermute_b32 v222, v228, v196
	ds_bpermute_b32 v223, v228, v197
	ds_bpermute_b32 v224, v228, v204
	ds_bpermute_b32 v225, v228, v205
	ds_bpermute_b32 v226, v228, v206
	ds_bpermute_b32 v227, v228, v207
	s_waitcnt lgkmcnt(7)
	v_add_f32_e32 v194, v194, v220
	s_waitcnt lgkmcnt(6)
	v_add_f32_e32 v195, v195, v221
	s_waitcnt lgkmcnt(5)
	v_add_f32_e32 v196, v196, v222
	s_waitcnt lgkmcnt(4)
	v_add_f32_e32 v197, v197, v223
	s_waitcnt lgkmcnt(3)
	v_add_f32_e32 v204, v204, v224
	s_waitcnt lgkmcnt(2)
	v_add_f32_e32 v205, v205, v225
	s_waitcnt lgkmcnt(1)
	v_add_f32_e32 v206, v206, v226
	s_waitcnt lgkmcnt(0)
	v_add_f32_e32 v207, v207, v227
	ds_bpermute_b32 v220, v229, v194
	ds_bpermute_b32 v221, v229, v195
	ds_bpermute_b32 v222, v229, v196
	ds_bpermute_b32 v223, v229, v197
	ds_bpermute_b32 v224, v229, v204
	ds_bpermute_b32 v225, v229, v205
	ds_bpermute_b32 v226, v229, v206
	ds_bpermute_b32 v227, v229, v207
	s_waitcnt lgkmcnt(7)
	v_add_f32_e32 v194, v194, v220
	s_waitcnt lgkmcnt(6)
	v_add_f32_e32 v195, v195, v221
	s_waitcnt lgkmcnt(5)
	v_add_f32_e32 v196, v196, v222
	s_waitcnt lgkmcnt(4)
	v_add_f32_e32 v197, v197, v223
	s_waitcnt lgkmcnt(3)
	v_add_f32_e32 v204, v204, v224
	s_waitcnt lgkmcnt(2)
	v_add_f32_e32 v205, v205, v225
	s_waitcnt lgkmcnt(1)
	v_add_f32_e32 v206, v206, v226
	s_waitcnt lgkmcnt(0)
	v_add_f32_e32 v207, v207, v227
	v_fmamk_f32 v194, v194, 0x3a800000, v208
	v_fmamk_f32 v195, v195, 0x3a800000, v208
	v_fmamk_f32 v196, v196, 0x3a800000, v208
	v_fmamk_f32 v197, v197, 0x3a800000, v208
	v_fmamk_f32 v204, v204, 0x3a800000, v208
	v_fmamk_f32 v205, v205, 0x3a800000, v208
	v_fmamk_f32 v206, v206, 0x3a800000, v208
	v_fmamk_f32 v207, v207, 0x3a800000, v208
	v_rsq_f32_e32 v152, v194
	v_rsq_f32_e32 v156, v195
	v_rsq_f32_e32 v160, v196
	v_rsq_f32_e32 v164, v197
	v_rsq_f32_e32 v168, v204
	v_rsq_f32_e32 v172, v205
	v_rsq_f32_e32 v176, v206
	v_rsq_f32_e32 v180, v207
	v_mov_b32_e32 v220, 1.0
	v_mul_f32_e32 v154, 0xbfb8aa3b, v152
	v_mul_f32_e32 v152, v152, v152
	v_pk_mul_f32 v[124:125], v[128:129], v[124:125]
	v_pk_mul_f32 v[126:127], v[130:131], v[126:127]
	v_pk_mul_f32 v[116:117], v[120:121], v[116:117]
	v_pk_mul_f32 v[118:119], v[122:123], v[118:119]
	v_pk_mul_f32 v[128:129], v[128:129], v[154:155] op_sel_hi:[1,0]
	v_pk_mul_f32 v[130:131], v[130:131], v[154:155] op_sel_hi:[1,0]
	v_pk_mul_f32 v[120:121], v[120:121], v[154:155] op_sel_hi:[1,0]
	v_pk_mul_f32 v[122:123], v[122:123], v[154:155] op_sel_hi:[1,0]
	v_pk_mul_f32 v[124:125], v[124:125], v[152:153] op_sel_hi:[1,0]
	v_pk_mul_f32 v[126:127], v[126:127], v[152:153] op_sel_hi:[1,0]
	v_pk_mul_f32 v[116:117], v[116:117], v[152:153] op_sel_hi:[1,0]
	v_pk_mul_f32 v[118:119], v[118:119], v[152:153] op_sel_hi:[1,0]
	v_exp_f32_e32 v128, v128
	v_exp_f32_e32 v129, v129
	v_exp_f32_e32 v130, v130
	v_exp_f32_e32 v131, v131
	v_exp_f32_e32 v120, v120
	v_exp_f32_e32 v121, v121
	v_exp_f32_e32 v122, v122
	v_exp_f32_e32 v123, v123
	v_pk_add_f32 v[128:129], v[128:129], v[220:221] op_sel_hi:[1,0]
	v_pk_add_f32 v[130:131], v[130:131], v[220:221] op_sel_hi:[1,0]
	v_pk_add_f32 v[120:121], v[120:121], v[220:221] op_sel_hi:[1,0]
	v_pk_add_f32 v[122:123], v[122:123], v[220:221] op_sel_hi:[1,0]
	v_rcp_f32_e32 v128, v128
	v_rcp_f32_e32 v129, v129
	v_rcp_f32_e32 v130, v130
	v_rcp_f32_e32 v131, v131
	v_rcp_f32_e32 v120, v120
	v_rcp_f32_e32 v121, v121
	v_rcp_f32_e32 v122, v122
	v_rcp_f32_e32 v123, v123
	v_pk_mul_f32 v[128:129], v[124:125], v[128:129]
; __device__ __forceinline__ unsigned cvt_pk_bf16(float lo, float hi) { unsigned r; asm volatile("v_cvt_pk_bf16_f32 %0, %1, %2" : "=v"(r) : "v"(lo), "v"(hi)); return r; }
;     __device__ __forceinline__ void operator()(const f32x4 (&acc)[2][2][4][2], const Unit& u, int wr, int wc, int fr, int fq) const {
;     ...
;             for (int m = 0; m < 4; ++m) { const int row = row0 + ai * HALF + m * 16; const f32x4 q0 = *(const f32x4*)(ssq + (size_t)row * 16), q1 = *(const f32x4*)(ssq + (size_t)row * 16 + 4), q2 = *(const f32x4*)(ssq + (size_t)row * 16 + 8), q3 = *(const f32x4*)(ssq + (size_t)row * 16 + 12);
;                 const float rs = rsqrtf(((((q0[0] + q0[1]) + (q0[2] + q0[3])) + ((q1[0] + q1[1]) + (q1[2] + q1[3]))) + (((q2[0] + q2[1]) + (q2[2] + q2[3])) + ((q3[0] + q3[1]) + (q3[2] + q3[3])))) * (1.0f / 1024.0f) + 1e-6f);
;                 float a[8];
; #pragma unroll
;                 for (int n = 0; n < 2; ++n)
; #pragma unroll
;                     for (int j = 0; j < 4; ++j) { const float g = acc[ai][0][m][n][j] * rs, up = acc[ai][1][m][n][j] * rs; a[4 * n + j] = g * up * __builtin_amdgcn_rcpf(1.0f + __expf(-g)); }
;                 u32x4 w; w.x = cvt_pk_bf16(a[0], a[1]); w.y = cvt_pk_bf16(a[2], a[3]); w.z = cvt_pk_bf16(a[4], a[5]); w.w = cvt_pk_bf16(a[6], a[7]);
;                 *(u32x4*)(O + (size_t)row * ldc + col0) = w; }
	v_pk_mul_f32 v[130:131], v[126:127], v[130:131]
	v_pk_mul_f32 v[120:121], v[116:117], v[120:121]
	v_pk_mul_f32 v[122:123], v[118:119], v[122:123]
	v_cvt_pk_bf16_f32 v128, v128, v129
	v_cvt_pk_bf16_f32 v129, v130, v131
	v_cvt_pk_bf16_f32 v130, v120, v121
	v_cvt_pk_bf16_f32 v131, v122, v123
	global_store_dwordx4 v184, v[128:131], s[28:29]
	v_mul_f32_e32 v158, 0xbfb8aa3b, v156
	v_mul_f32_e32 v156, v156, v156
	v_pk_mul_f32 v[108:109], v[112:113], v[108:109]
	v_pk_mul_f32 v[110:111], v[114:115], v[110:111]
	v_pk_mul_f32 v[100:101], v[104:105], v[100:101]
	v_pk_mul_f32 v[102:103], v[106:107], v[102:103]
	v_pk_mul_f32 v[112:113], v[112:113], v[158:159] op_sel_hi:[1,0]
	v_pk_mul_f32 v[114:115], v[114:115], v[158:159] op_sel_hi:[1,0]
	v_pk_mul_f32 v[104:105], v[104:105], v[158:159] op_sel_hi:[1,0]
	v_pk_mul_f32 v[106:107], v[106:107], v[158:159] op_sel_hi:[1,0]
	v_pk_mul_f32 v[108:109], v[108:109], v[156:157] op_sel_hi:[1,0]
	v_pk_mul_f32 v[110:111], v[110:111], v[156:157] op_sel_hi:[1,0]
	v_pk_mul_f32 v[100:101], v[100:101], v[156:157] op_sel_hi:[1,0]
	v_pk_mul_f32 v[102:103], v[102:103], v[156:157] op_sel_hi:[1,0]
	v_exp_f32_e32 v112, v112
	v_exp_f32_e32 v113, v113
	v_exp_f32_e32 v114, v114
	v_exp_f32_e32 v115, v115
	v_exp_f32_e32 v104, v104
	v_exp_f32_e32 v105, v105
	v_exp_f32_e32 v106, v106
	v_exp_f32_e32 v107, v107
	v_pk_add_f32 v[112:113], v[112:113], v[220:221] op_sel_hi:[1,0]
	v_pk_add_f32 v[114:115], v[114:115], v[220:221] op_sel_hi:[1,0]
	v_pk_add_f32 v[104:105], v[104:105], v[220:221] op_sel_hi:[1,0]
	v_pk_add_f32 v[106:107], v[106:107], v[220:221] op_sel_hi:[1,0]
	v_rcp_f32_e32 v112, v112
	v_rcp_f32_e32 v113, v113
	v_rcp_f32_e32 v114, v114
	v_rcp_f32_e32 v115, v115
	v_rcp_f32_e32 v104, v104
	v_rcp_f32_e32 v105, v105
	v_rcp_f32_e32 v106, v106
	v_rcp_f32_e32 v107, v107
	v_pk_mul_f32 v[112:113], v[108:109], v[112:113]
	v_pk_mul_f32 v[114:115], v[110:111], v[114:115]
	v_pk_mul_f32 v[104:105], v[100:101], v[104:105]
	v_pk_mul_f32 v[106:107], v[102:103], v[106:107]
	v_cvt_pk_bf16_f32 v112, v112, v113
	v_cvt_pk_bf16_f32 v113, v114, v115
	v_cvt_pk_bf16_f32 v114, v104, v105
	v_cvt_pk_bf16_f32 v115, v106, v107
	global_store_dwordx4 v185, v[112:115], s[28:29]
	v_mul_f32_e32 v162, 0xbfb8aa3b, v160
	v_mul_f32_e32 v160, v160, v160
	v_pk_mul_f32 v[92:93], v[96:97], v[92:93]
	v_pk_mul_f32 v[94:95], v[98:99], v[94:95]
	v_pk_mul_f32 v[84:85], v[88:89], v[84:85]
	v_pk_mul_f32 v[86:87], v[90:91], v[86:87]
	v_pk_mul_f32 v[96:97], v[96:97], v[162:163] op_sel_hi:[1,0]
	v_pk_mul_f32 v[98:99], v[98:99], v[162:163] op_sel_hi:[1,0]
	v_pk_mul_f32 v[88:89], v[88:89], v[162:163] op_sel_hi:[1,0]
	v_pk_mul_f32 v[90:91], v[90:91], v[162:163] op_sel_hi:[1,0]
	v_pk_mul_f32 v[92:93], v[92:93], v[160:161] op_sel_hi:[1,0]
	v_pk_mul_f32 v[94:95], v[94:95], v[160:161] op_sel_hi:[1,0]
	v_pk_mul_f32 v[84:85], v[84:85], v[160:161] op_sel_hi:[1,0]
	v_pk_mul_f32 v[86:87], v[86:87], v[160:161] op_sel_hi:[1,0]
	v_exp_f32_e32 v96, v96
	v_exp_f32_e32 v97, v97
	v_exp_f32_e32 v98, v98
	v_exp_f32_e32 v99, v99
	v_exp_f32_e32 v88, v88
	v_exp_f32_e32 v89, v89
	v_exp_f32_e32 v90, v90
	v_exp_f32_e32 v91, v91
	v_pk_add_f32 v[96:97], v[96:97], v[220:221] op_sel_hi:[1,0]
	v_pk_add_f32 v[98:99], v[98:99], v[220:221] op_sel_hi:[1,0]
	v_pk_add_f32 v[88:89], v[88:89], v[220:221] op_sel_hi:[1,0]
	v_pk_add_f32 v[90:91], v[90:91], v[220:221] op_sel_hi:[1,0]
	v_rcp_f32_e32 v96, v96
	v_rcp_f32_e32 v97, v97
	v_rcp_f32_e32 v98, v98
	v_rcp_f32_e32 v99, v99
	v_rcp_f32_e32 v88, v88
	v_rcp_f32_e32 v89, v89
	v_rcp_f32_e32 v90, v90
	v_rcp_f32_e32 v91, v91
	v_pk_mul_f32 v[96:97], v[92:93], v[96:97]
	v_pk_mul_f32 v[98:99], v[94:95], v[98:99]
	v_pk_mul_f32 v[88:89], v[84:85], v[88:89]
	v_pk_mul_f32 v[90:91], v[86:87], v[90:91]
	v_cvt_pk_bf16_f32 v96, v96, v97
	v_cvt_pk_bf16_f32 v97, v98, v99
	v_cvt_pk_bf16_f32 v98, v88, v89
	v_cvt_pk_bf16_f32 v99, v90, v91
	global_store_dwordx4 v186, v[96:99], s[28:29]
	v_mul_f32_e32 v166, 0xbfb8aa3b, v164
	v_mul_f32_e32 v164, v164, v164
	v_pk_mul_f32 v[76:77], v[80:81], v[76:77]
	v_pk_mul_f32 v[78:79], v[82:83], v[78:79]
	v_pk_mul_f32 v[68:69], v[72:73], v[68:69]
	v_pk_mul_f32 v[70:71], v[74:75], v[70:71]
	v_pk_mul_f32 v[80:81], v[80:81], v[166:167] op_sel_hi:[1,0]
	v_pk_mul_f32 v[82:83], v[82:83], v[166:167] op_sel_hi:[1,0]
	v_pk_mul_f32 v[72:73], v[72:73], v[166:167] op_sel_hi:[1,0]
	v_pk_mul_f32 v[74:75], v[74:75], v[166:167] op_sel_hi:[1,0]
	v_pk_mul_f32 v[76:77], v[76:77], v[164:165] op_sel_hi:[1,0]
	v_pk_mul_f32 v[78:79], v[78:79], v[164:165] op_sel_hi:[1,0]
	v_pk_mul_f32 v[68:69], v[68:69], v[164:165] op_sel_hi:[1,0]
	v_pk_mul_f32 v[70:71], v[70:71], v[164:165] op_sel_hi:[1,0]
	v_exp_f32_e32 v80, v80
	v_exp_f32_e32 v81, v81
	v_exp_f32_e32 v82, v82
	v_exp_f32_e32 v83, v83
	v_exp_f32_e32 v72, v72
	v_exp_f32_e32 v73, v73
	v_exp_f32_e32 v74, v74
	v_exp_f32_e32 v75, v75
	v_pk_add_f32 v[80:81], v[80:81], v[220:221] op_sel_hi:[1,0]
	v_pk_add_f32 v[82:83], v[82:83], v[220:221] op_sel_hi:[1,0]
	v_pk_add_f32 v[72:73], v[72:73], v[220:221] op_sel_hi:[1,0]
	v_pk_add_f32 v[74:75], v[74:75], v[220:221] op_sel_hi:[1,0]
	v_rcp_f32_e32 v80, v80
	v_rcp_f32_e32 v81, v81
	v_rcp_f32_e32 v82, v82
	v_rcp_f32_e32 v83, v83
	v_rcp_f32_e32 v72, v72
	v_rcp_f32_e32 v73, v73
	v_rcp_f32_e32 v74, v74
	v_rcp_f32_e32 v75, v75
	v_pk_mul_f32 v[80:81], v[76:77], v[80:81]
	v_pk_mul_f32 v[82:83], v[78:79], v[82:83]
	v_pk_mul_f32 v[72:73], v[68:69], v[72:73]
	v_pk_mul_f32 v[74:75], v[70:71], v[74:75]
	v_cvt_pk_bf16_f32 v80, v80, v81
	v_cvt_pk_bf16_f32 v81, v82, v83
	v_cvt_pk_bf16_f32 v82, v72, v73
	v_cvt_pk_bf16_f32 v83, v74, v75
	global_store_dwordx4 v187, v[80:83], s[28:29]
	v_mul_f32_e32 v170, 0xbfb8aa3b, v168
; __device__ __forceinline__ unsigned cvt_pk_bf16(float lo, float hi) { unsigned r; asm volatile("v_cvt_pk_bf16_f32 %0, %1, %2" : "=v"(r) : "v"(lo), "v"(hi)); return r; }
;     __device__ __forceinline__ void operator()(const f32x4 (&acc)[2][2][4][2], const Unit& u, int wr, int wc, int fr, int fq) const {
;     ...
;             for (int m = 0; m < 4; ++m) { const int row = row0 + ai * HALF + m * 16; const f32x4 q0 = *(const f32x4*)(ssq + (size_t)row * 16), q1 = *(const f32x4*)(ssq + (size_t)row * 16 + 4), q2 = *(const f32x4*)(ssq + (size_t)row * 16 + 8), q3 = *(const f32x4*)(ssq + (size_t)row * 16 + 12);
;                 const float rs = rsqrtf(((((q0[0] + q0[1]) + (q0[2] + q0[3])) + ((q1[0] + q1[1]) + (q1[2] + q1[3]))) + (((q2[0] + q2[1]) + (q2[2] + q2[3])) + ((q3[0] + q3[1]) + (q3[2] + q3[3])))) * (1.0f / 1024.0f) + 1e-6f);
;                 float a[8];
; #pragma unroll
;                 for (int n = 0; n < 2; ++n)
; #pragma unroll
;                     for (int j = 0; j < 4; ++j) { const float g = acc[ai][0][m][n][j] * rs, up = acc[ai][1][m][n][j] * rs; a[4 * n + j] = g * up * __builtin_amdgcn_rcpf(1.0f + __expf(-g)); }
;                 u32x4 w; w.x = cvt_pk_bf16(a[0], a[1]); w.y = cvt_pk_bf16(a[2], a[3]); w.z = cvt_pk_bf16(a[4], a[5]); w.w = cvt_pk_bf16(a[6], a[7]);
;                 *(u32x4*)(O + (size_t)row * ldc + col0) = w; }
	v_mul_f32_e32 v168, v168, v168
	v_pk_mul_f32 v[60:61], v[64:65], v[60:61]
	v_pk_mul_f32 v[62:63], v[66:67], v[62:63]
	v_pk_mul_f32 v[52:53], v[56:57], v[52:53]
	v_pk_mul_f32 v[54:55], v[58:59], v[54:55]
	v_pk_mul_f32 v[64:65], v[64:65], v[170:171] op_sel_hi:[1,0]
	v_pk_mul_f32 v[66:67], v[66:67], v[170:171] op_sel_hi:[1,0]
	v_pk_mul_f32 v[56:57], v[56:57], v[170:171] op_sel_hi:[1,0]
	v_pk_mul_f32 v[58:59], v[58:59], v[170:171] op_sel_hi:[1,0]
	v_pk_mul_f32 v[60:61], v[60:61], v[168:169] op_sel_hi:[1,0]
	v_pk_mul_f32 v[62:63], v[62:63], v[168:169] op_sel_hi:[1,0]
	v_pk_mul_f32 v[52:53], v[52:53], v[168:169] op_sel_hi:[1,0]
	v_pk_mul_f32 v[54:55], v[54:55], v[168:169] op_sel_hi:[1,0]
	v_exp_f32_e32 v64, v64
	v_exp_f32_e32 v65, v65
	v_exp_f32_e32 v66, v66
	v_exp_f32_e32 v67, v67
	v_exp_f32_e32 v56, v56
	v_exp_f32_e32 v57, v57
	v_exp_f32_e32 v58, v58
	v_exp_f32_e32 v59, v59
	v_pk_add_f32 v[64:65], v[64:65], v[220:221] op_sel_hi:[1,0]
	v_pk_add_f32 v[66:67], v[66:67], v[220:221] op_sel_hi:[1,0]
	v_pk_add_f32 v[56:57], v[56:57], v[220:221] op_sel_hi:[1,0]
	v_pk_add_f32 v[58:59], v[58:59], v[220:221] op_sel_hi:[1,0]
	v_rcp_f32_e32 v64, v64
	v_rcp_f32_e32 v65, v65
	v_rcp_f32_e32 v66, v66
	v_rcp_f32_e32 v67, v67
	v_rcp_f32_e32 v56, v56
	v_rcp_f32_e32 v57, v57
	v_rcp_f32_e32 v58, v58
	v_rcp_f32_e32 v59, v59
	v_pk_mul_f32 v[64:65], v[60:61], v[64:65]
	v_pk_mul_f32 v[66:67], v[62:63], v[66:67]
	v_pk_mul_f32 v[56:57], v[52:53], v[56:57]
	v_pk_mul_f32 v[58:59], v[54:55], v[58:59]
	v_cvt_pk_bf16_f32 v64, v64, v65
	v_cvt_pk_bf16_f32 v65, v66, v67
	v_cvt_pk_bf16_f32 v66, v56, v57
	v_cvt_pk_bf16_f32 v67, v58, v59
	global_store_dwordx4 v188, v[64:67], s[28:29]
	v_mul_f32_e32 v174, 0xbfb8aa3b, v172
	v_mul_f32_e32 v172, v172, v172
	v_pk_mul_f32 v[44:45], v[48:49], v[44:45]
	v_pk_mul_f32 v[46:47], v[50:51], v[46:47]
	v_pk_mul_f32 v[36:37], v[40:41], v[36:37]
	v_pk_mul_f32 v[38:39], v[42:43], v[38:39]
	v_pk_mul_f32 v[48:49], v[48:49], v[174:175] op_sel_hi:[1,0]
	v_pk_mul_f32 v[50:51], v[50:51], v[174:175] op_sel_hi:[1,0]
	v_pk_mul_f32 v[40:41], v[40:41], v[174:175] op_sel_hi:[1,0]
	v_pk_mul_f32 v[42:43], v[42:43], v[174:175] op_sel_hi:[1,0]
	v_pk_mul_f32 v[44:45], v[44:45], v[172:173] op_sel_hi:[1,0]
	v_pk_mul_f32 v[46:47], v[46:47], v[172:173] op_sel_hi:[1,0]
	v_pk_mul_f32 v[36:37], v[36:37], v[172:173] op_sel_hi:[1,0]
	v_pk_mul_f32 v[38:39], v[38:39], v[172:173] op_sel_hi:[1,0]
	v_exp_f32_e32 v48, v48
	v_exp_f32_e32 v49, v49
	v_exp_f32_e32 v50, v50
	v_exp_f32_e32 v51, v51
	v_exp_f32_e32 v40, v40
	v_exp_f32_e32 v41, v41
	v_exp_f32_e32 v42, v42
	v_exp_f32_e32 v43, v43
	v_pk_add_f32 v[48:49], v[48:49], v[220:221] op_sel_hi:[1,0]
	v_pk_add_f32 v[50:51], v[50:51], v[220:221] op_sel_hi:[1,0]
	v_pk_add_f32 v[40:41], v[40:41], v[220:221] op_sel_hi:[1,0]
	v_pk_add_f32 v[42:43], v[42:43], v[220:221] op_sel_hi:[1,0]
	v_rcp_f32_e32 v48, v48
	v_rcp_f32_e32 v49, v49
	v_rcp_f32_e32 v50, v50
	v_rcp_f32_e32 v51, v51
	v_rcp_f32_e32 v40, v40
	v_rcp_f32_e32 v41, v41
	v_rcp_f32_e32 v42, v42
	v_rcp_f32_e32 v43, v43
	v_pk_mul_f32 v[48:49], v[44:45], v[48:49]
	v_pk_mul_f32 v[50:51], v[46:47], v[50:51]
	v_pk_mul_f32 v[40:41], v[36:37], v[40:41]
	v_pk_mul_f32 v[42:43], v[38:39], v[42:43]
	v_cvt_pk_bf16_f32 v48, v48, v49
	v_cvt_pk_bf16_f32 v49, v50, v51
	v_cvt_pk_bf16_f32 v50, v40, v41
	v_cvt_pk_bf16_f32 v51, v42, v43
	global_store_dwordx4 v189, v[48:51], s[28:29]
	v_mul_f32_e32 v178, 0xbfb8aa3b, v176
	v_mul_f32_e32 v176, v176, v176
	v_pk_mul_f32 v[28:29], v[32:33], v[28:29]
	v_pk_mul_f32 v[30:31], v[34:35], v[30:31]
	v_pk_mul_f32 v[20:21], v[24:25], v[20:21]
	v_pk_mul_f32 v[22:23], v[26:27], v[22:23]
	v_pk_mul_f32 v[32:33], v[32:33], v[178:179] op_sel_hi:[1,0]
	v_pk_mul_f32 v[34:35], v[34:35], v[178:179] op_sel_hi:[1,0]
	v_pk_mul_f32 v[24:25], v[24:25], v[178:179] op_sel_hi:[1,0]
	v_pk_mul_f32 v[26:27], v[26:27], v[178:179] op_sel_hi:[1,0]
	v_pk_mul_f32 v[28:29], v[28:29], v[176:177] op_sel_hi:[1,0]
	v_pk_mul_f32 v[30:31], v[30:31], v[176:177] op_sel_hi:[1,0]
	v_pk_mul_f32 v[20:21], v[20:21], v[176:177] op_sel_hi:[1,0]
	v_pk_mul_f32 v[22:23], v[22:23], v[176:177] op_sel_hi:[1,0]
	v_exp_f32_e32 v32, v32
	v_exp_f32_e32 v33, v33
	v_exp_f32_e32 v34, v34
	v_exp_f32_e32 v35, v35
	v_exp_f32_e32 v24, v24
	v_exp_f32_e32 v25, v25
	v_exp_f32_e32 v26, v26
	v_exp_f32_e32 v27, v27
	v_pk_add_f32 v[32:33], v[32:33], v[220:221] op_sel_hi:[1,0]
	v_pk_add_f32 v[34:35], v[34:35], v[220:221] op_sel_hi:[1,0]
	v_pk_add_f32 v[24:25], v[24:25], v[220:221] op_sel_hi:[1,0]
	v_pk_add_f32 v[26:27], v[26:27], v[220:221] op_sel_hi:[1,0]
	v_rcp_f32_e32 v32, v32
	v_rcp_f32_e32 v33, v33
	v_rcp_f32_e32 v34, v34
	v_rcp_f32_e32 v35, v35
	v_rcp_f32_e32 v24, v24
	v_rcp_f32_e32 v25, v25
	v_rcp_f32_e32 v26, v26
	v_rcp_f32_e32 v27, v27
	v_pk_mul_f32 v[32:33], v[28:29], v[32:33]
	v_pk_mul_f32 v[34:35], v[30:31], v[34:35]
	v_pk_mul_f32 v[24:25], v[20:21], v[24:25]
	v_pk_mul_f32 v[26:27], v[22:23], v[26:27]
	v_cvt_pk_bf16_f32 v32, v32, v33
	v_cvt_pk_bf16_f32 v33, v34, v35
	v_cvt_pk_bf16_f32 v34, v24, v25
	v_cvt_pk_bf16_f32 v35, v26, v27
	global_store_dwordx4 v190, v[32:35], s[28:29]
	v_mul_f32_e32 v182, 0xbfb8aa3b, v180
	v_mul_f32_e32 v180, v180, v180
	v_pk_mul_f32 v[12:13], v[16:17], v[12:13]
	v_pk_mul_f32 v[14:15], v[18:19], v[14:15]
	v_pk_mul_f32 v[4:5], v[8:9], v[4:5]
	v_pk_mul_f32 v[6:7], v[10:11], v[6:7]
	v_pk_mul_f32 v[16:17], v[16:17], v[182:183] op_sel_hi:[1,0]
	v_pk_mul_f32 v[18:19], v[18:19], v[182:183] op_sel_hi:[1,0]
	v_pk_mul_f32 v[8:9], v[8:9], v[182:183] op_sel_hi:[1,0]
	v_pk_mul_f32 v[10:11], v[10:11], v[182:183] op_sel_hi:[1,0]
	v_pk_mul_f32 v[12:13], v[12:13], v[180:181] op_sel_hi:[1,0]
	v_pk_mul_f32 v[14:15], v[14:15], v[180:181] op_sel_hi:[1,0]
	v_pk_mul_f32 v[4:5], v[4:5], v[180:181] op_sel_hi:[1,0]
	v_pk_mul_f32 v[6:7], v[6:7], v[180:181] op_sel_hi:[1,0]
	v_exp_f32_e32 v16, v16
	v_exp_f32_e32 v17, v17
	v_exp_f32_e32 v18, v18
	v_exp_f32_e32 v19, v19
	v_exp_f32_e32 v8, v8
	v_exp_f32_e32 v9, v9
	v_exp_f32_e32 v10, v10
	v_exp_f32_e32 v11, v11
	v_pk_add_f32 v[16:17], v[16:17], v[220:221] op_sel_hi:[1,0]
	v_pk_add_f32 v[18:19], v[18:19], v[220:221] op_sel_hi:[1,0]
	v_pk_add_f32 v[8:9], v[8:9], v[220:221] op_sel_hi:[1,0]
	v_pk_add_f32 v[10:11], v[10:11], v[220:221] op_sel_hi:[1,0]
	v_rcp_f32_e32 v16, v16
	v_rcp_f32_e32 v17, v17
	v_rcp_f32_e32 v18, v18
	v_rcp_f32_e32 v19, v19
	v_rcp_f32_e32 v8, v8
	v_rcp_f32_e32 v9, v9
	v_rcp_f32_e32 v10, v10
	v_rcp_f32_e32 v11, v11
	v_pk_mul_f32 v[16:17], v[12:13], v[16:17]
	v_pk_mul_f32 v[18:19], v[14:15], v[18:19]
	v_pk_mul_f32 v[8:9], v[4:5], v[8:9]
	v_pk_mul_f32 v[10:11], v[6:7], v[10:11]
	v_cvt_pk_bf16_f32 v16, v16, v17
	v_cvt_pk_bf16_f32 v17, v18, v19
	v_cvt_pk_bf16_f32 v18, v8, v9
	v_cvt_pk_bf16_f32 v19, v10, v11
	global_store_dwordx4 v191, v[16:19], s[28:29]
	s_mov_b32 s23, 0x800000
	v_readlane_b32 s60, v253, 3
	s_mov_b32 s99, 0x800000
	v_readlane_b32 s61, v253, 4
	v_readlane_b32 s62, v253, 5
	v_readlane_b32 s63, v253, 6
	s_andn2_b64 vcc, exec, s[2:3]
	s_mov_b64 s[28:29], -1
	s_cbranch_vccnz .LBB0_603
; #define PG8_BAR __builtin_amdgcn_s_barrier()
; template <class Epi, class Sched, bool ALIGN_EPI = false, bool SP2 = false>
; __device__ __forceinline__ void gemm_phase(PG8_LAS unsigned char* lds, const Gemm g, const Sched& S, const Epi& E) {
;     ...
;         if constexpr (ALIGN_EPI) { if (wr == 1) PG8_BAR; }
;     }
	s_andn2_b64 vcc, exec, s[14:15]
	s_cbranch_vccnz .LBB0_602
	s_barrier
	s_branch .LBB0_602

; #define PG8_STAGE(bufoff, gbase, voff) do { _Pragma("unroll") for (int _i = 0; _i < 2; ++_i) \
;         __builtin_amdgcn_global_load_lds((const unsigned*)((const char*)(gbase) + (voff)[_i]), (PG8_LAS unsigned*)(lds + (bufoff) + ldsw + _i * 8192), 16, 0, 0); } while (0)
; #define PG8_LDA(dst, b, h) do { _Pragma("unroll") for (int m = 0; m < 4; ++m) _Pragma("unroll") for (int k = 0; k < 2; ++k) dst[m][k] = *(const PG8_LAS bf16x8*)(lds + PG8_SA(b, h) + aoff + m * 2048 + k * 1024); } while (0)
; #define PG8_LDB(dst, b, h) do { _Pragma("unroll") for (int n = 0; n < 2; ++n) _Pragma("unroll") for (int k = 0; k < 2; ++k) dst[n][k] = *(const PG8_LAS bf16x8*)(lds + PG8_SB(b, h) + boff + n * 2048 + k * 1024); } while (0)
; #define PG8_MMA(ai, bj, At, Bt) do { __builtin_amdgcn_s_setprio(1); _Pragma("unroll") for (int m = 0; m < 4; ++m) _Pragma("unroll") for (int n = 0; n < 2; ++n) _Pragma("unroll") for (int k = 0; k < 2; ++k) \
;         acc[ai][bj][m][n] = __builtin_amdgcn_mfma_f32_16x16x32_bf16(Bt[n][k], At[m][k], acc[ai][bj][m][n], 0, 0, 0); __builtin_amdgcn_s_setprio(0); } while (0)
; #define PG8_WAIT_V(n) asm volatile("s_waitcnt vmcnt(" #n ")" ::: "memory")
; template <class Epi, class Sched, bool ALIGN_EPI = false, bool SP2 = false>
; __device__ __forceinline__ void gemm_phase(PG8_LAS unsigned char* lds, const Gemm g, const Sched& S, const Epi& E) {
;     ...
;         for (int t = 0; t < nt; t += 2) {
;             const bool last = (t == nt - 2);
;             const char* a1 = cA + (size_t)(t + 1) * kstep;
;             const char* a2 = last ? nA : cA + (size_t)(t + 2) * kstep; const char* b2 = last ? nB : cB + (size_t)(t + 2) * kstep;
;             const char* a3 = a2 + kstep; const char* b3 = b2 + kstep;
;             if (last && has_next) S.a_ready(nxt);
;             if constexpr (SP2) {
;             PG8_LDB(B0, 0, 0); PG8_LDB(B1, 0, 1); PG8_SCHED; PG8_LDA(At, 0, 0); PG8_STAGE(PG8_SA(1, 1), a1 + hstep, voffA);
;             PG8_WAIT_V(8); PG8_WAIT_L(0); PG8_BAR; PG8_MMA(0, 0, At, B0); PG8_MMA(0, 1, At, B1); PG8_BAR; PG8_SCHED;
;     ...
;         for (int a = 0; a < 2; ++a)
; #pragma unroll
;             for (int b = 0; b < 2; ++b)
; #pragma unroll
;                 for (int m = 0; m < 4; ++m)
; #pragma unroll
;                     for (int n = 0; n < 2; ++n) acc[a][b][m][n] = (f32x4){0.f, 0.f, 0.f, 0.f};
;         cur = nxt; cA = nA; cB = nB; ++ui;
.LBB0_637:
	s_add_u32 s26, s26, 0x80
	s_addc_u32 s27, s27, 0
	s_add_u32 s33, s28, 0x100
	s_addc_u32 s54, s29, 0
	s_mov_b32 s28, 0
	s_waitcnt lgkmcnt(0)
	v_mov_b64_e32 v[4:5], 0
	v_mov_b64_e32 v[6:7], 0
	v_mov_b64_e32 v[8:9], 0
	v_mov_b64_e32 v[10:11], 0
	v_mov_b64_e32 v[12:13], 0
	v_mov_b64_e32 v[14:15], 0
	v_mov_b64_e32 v[16:17], 0
	v_mov_b64_e32 v[18:19], 0
	v_mov_b64_e32 v[20:21], 0
	v_mov_b64_e32 v[22:23], 0
	v_mov_b64_e32 v[24:25], 0
	v_mov_b64_e32 v[26:27], 0
	v_mov_b64_e32 v[28:29], 0
	v_mov_b64_e32 v[30:31], 0
	v_mov_b64_e32 v[32:33], 0
	v_mov_b64_e32 v[34:35], 0
	v_mov_b64_e32 v[36:37], 0
	v_mov_b64_e32 v[38:39], 0
	v_mov_b64_e32 v[40:41], 0
	v_mov_b64_e32 v[42:43], 0
	v_mov_b64_e32 v[44:45], 0
	v_mov_b64_e32 v[46:47], 0
	v_mov_b64_e32 v[48:49], 0
	v_mov_b64_e32 v[50:51], 0
	v_mov_b64_e32 v[52:53], 0
	v_mov_b64_e32 v[54:55], 0
	v_mov_b64_e32 v[56:57], 0
	v_mov_b64_e32 v[58:59], 0
	v_mov_b64_e32 v[60:61], 0
	v_mov_b64_e32 v[62:63], 0
	v_mov_b64_e32 v[64:65], 0
	v_mov_b64_e32 v[66:67], 0
	v_mov_b64_e32 v[68:69], 0
	v_mov_b64_e32 v[70:71], 0
	v_mov_b64_e32 v[72:73], 0
	v_mov_b64_e32 v[74:75], 0
	v_mov_b64_e32 v[76:77], 0
	v_mov_b64_e32 v[78:79], 0
	v_mov_b64_e32 v[80:81], 0
	v_mov_b64_e32 v[82:83], 0
	v_mov_b64_e32 v[84:85], 0
	v_mov_b64_e32 v[86:87], 0
	v_mov_b64_e32 v[88:89], 0
	v_mov_b64_e32 v[90:91], 0
	v_mov_b64_e32 v[92:93], 0
	v_mov_b64_e32 v[94:95], 0
	v_mov_b64_e32 v[96:97], 0
	v_mov_b64_e32 v[98:99], 0
	v_mov_b64_e32 v[100:101], 0
	v_mov_b64_e32 v[102:103], 0
	v_mov_b64_e32 v[104:105], 0
	v_mov_b64_e32 v[106:107], 0
	v_mov_b64_e32 v[108:109], 0
	v_mov_b64_e32 v[110:111], 0
	v_mov_b64_e32 v[112:113], 0
	v_mov_b64_e32 v[114:115], 0
	v_mov_b64_e32 v[116:117], 0
	v_mov_b64_e32 v[118:119], 0
	v_mov_b64_e32 v[120:121], 0
	v_mov_b64_e32 v[122:123], 0
	v_mov_b64_e32 v[124:125], 0
	v_mov_b64_e32 v[126:127], 0
	v_mov_b64_e32 v[128:129], 0
	v_mov_b64_e32 v[130:131], 0
	v_readfirstlane_b32 s89, v0
	s_nop 3
	s_lshr_b32 s89, s89, 6
	s_cmp_lt_u32 s89, 4
	s_cbranch_scc0 .Lprio_done1
	s_setprio 1
.Lprio_done1:
.LBB0_638:
	s_add_i32 s55, s28, 2
	s_add_u32 s56, s26, 0x80
	s_addc_u32 s29, s27, 0
	s_add_i32 s58, 0, 0x10000
	s_cmp_eq_u32 s47, s28
	s_cselect_b32 s29, s7, s29
	s_cselect_b32 s28, s6, s56
	s_cselect_b32 s57, s25, s54
	s_cselect_b32 s56, s24, s33
	s_add_i32 s59, 0, 0x14000
	v_add_u32_e32 v158, s58, v147
	v_add_u32_e32 v174, s59, v147
	ds_read_b128 v[142:145], v158
	ds_read_b128 v[150:153], v158 offset:1024
	ds_read_b128 v[154:157], v158 offset:2048
	ds_read_b128 v[158:161], v158 offset:3072
	ds_read_b128 v[162:165], v174
	ds_read_b128 v[166:169], v174 offset:1024
	ds_read_b128 v[170:173], v174 offset:2048
	ds_read_b128 v[174:177], v174 offset:3072
	v_lshl_add_u64 v[194:195], s[26:27], 0, v[138:139]
	s_add_i32 m0, s34, 0xc000
	ds_read_b128 v[178:181], v149
	ds_read_b128 v[182:185], v149 offset:1024
	ds_read_b128 v[186:189], v149 offset:2048
	ds_read_b128 v[190:193], v149 offset:3072
	ds_read_b128 v[204:207], v149 offset:4096
	ds_read_b128 v[220:223], v149 offset:5120
	ds_read_b128 v[224:227], v149 offset:6144
	ds_read_b128 v[228:231], v149 offset:7168
	global_load_lds_dwordx4 v[194:195], off
	v_lshl_add_u64 v[194:195], s[26:27], 0, v[140:141]
	s_add_i32 m0, s34, 0xe000
	s_nop 0
	global_load_lds_dwordx4 v[194:195], off
	s_waitcnt vmcnt(8)
	s_waitcnt lgkmcnt(0)
	s_barrier
	s_waitcnt lgkmcnt(0)
	v_mfma_f32_16x16x32_bf16 v[128:131], v[142:145], v[178:181], v[128:131]
	v_mfma_f32_16x16x32_bf16 v[124:127], v[154:157], v[178:181], v[124:127]
	v_mfma_f32_16x16x32_bf16 v[112:115], v[142:145], v[186:189], v[112:115]
	v_mfma_f32_16x16x32_bf16 v[108:111], v[154:157], v[186:189], v[108:111]
	v_mfma_f32_16x16x32_bf16 v[96:99], v[142:145], v[204:207], v[96:99]
	v_mfma_f32_16x16x32_bf16 v[92:95], v[154:157], v[204:207], v[92:95]
	v_mfma_f32_16x16x32_bf16 v[80:83], v[142:145], v[224:227], v[80:83]
	v_mfma_f32_16x16x32_bf16 v[76:79], v[154:157], v[224:227], v[76:79]
	v_mfma_f32_16x16x32_bf16 v[128:131], v[150:153], v[182:185], v[128:131]
	v_mfma_f32_16x16x32_bf16 v[124:127], v[158:161], v[182:185], v[124:127]
	v_mfma_f32_16x16x32_bf16 v[112:115], v[150:153], v[190:193], v[112:115]
	v_mfma_f32_16x16x32_bf16 v[108:111], v[158:161], v[190:193], v[108:111]
	v_mfma_f32_16x16x32_bf16 v[96:99], v[150:153], v[220:223], v[96:99]
	v_mfma_f32_16x16x32_bf16 v[92:95], v[158:161], v[220:223], v[92:95]
	v_mfma_f32_16x16x32_bf16 v[80:83], v[150:153], v[228:231], v[80:83]
	v_mfma_f32_16x16x32_bf16 v[76:79], v[158:161], v[228:231], v[76:79]
	v_mfma_f32_16x16x32_bf16 v[120:123], v[162:165], v[178:181], v[120:123]
	v_mfma_f32_16x16x32_bf16 v[116:119], v[170:173], v[178:181], v[116:119]
	v_mfma_f32_16x16x32_bf16 v[104:107], v[162:165], v[186:189], v[104:107]
	v_mfma_f32_16x16x32_bf16 v[100:103], v[170:173], v[186:189], v[100:103]
	v_mfma_f32_16x16x32_bf16 v[88:91], v[162:165], v[204:207], v[88:91]
	v_mfma_f32_16x16x32_bf16 v[84:87], v[170:173], v[204:207], v[84:87]
	v_mfma_f32_16x16x32_bf16 v[72:75], v[162:165], v[224:227], v[72:75]
	v_mfma_f32_16x16x32_bf16 v[68:71], v[170:173], v[224:227], v[68:71]
	v_mfma_f32_16x16x32_bf16 v[120:123], v[166:169], v[182:185], v[120:123]
	v_mfma_f32_16x16x32_bf16 v[116:119], v[174:177], v[182:185], v[116:119]
	v_mfma_f32_16x16x32_bf16 v[104:107], v[166:169], v[190:193], v[104:107]
	v_mfma_f32_16x16x32_bf16 v[100:103], v[174:177], v[190:193], v[100:103]
	v_mfma_f32_16x16x32_bf16 v[88:91], v[166:169], v[220:223], v[88:91]
	v_mfma_f32_16x16x32_bf16 v[84:87], v[174:177], v[220:223], v[84:87]
	v_mfma_f32_16x16x32_bf16 v[72:75], v[166:169], v[228:231], v[72:75]
	v_mfma_f32_16x16x32_bf16 v[68:71], v[174:177], v[228:231], v[68:71]
	s_barrier
; #define PG8_STAGE(bufoff, gbase, voff) do { _Pragma("unroll") for (int _i = 0; _i < 2; ++_i) \
;         __builtin_amdgcn_global_load_lds((const unsigned*)((const char*)(gbase) + (voff)[_i]), (PG8_LAS unsigned*)(lds + (bufoff) + ldsw + _i * 8192), 16, 0, 0); } while (0)
; #define PG8_LDA(dst, b, h) do { _Pragma("unroll") for (int m = 0; m < 4; ++m) _Pragma("unroll") for (int k = 0; k < 2; ++k) dst[m][k] = *(const PG8_LAS bf16x8*)(lds + PG8_SA(b, h) + aoff + m * 2048 + k * 1024); } while (0)
; #define PG8_LDB(dst, b, h) do { _Pragma("unroll") for (int n = 0; n < 2; ++n) _Pragma("unroll") for (int k = 0; k < 2; ++k) dst[n][k] = *(const PG8_LAS bf16x8*)(lds + PG8_SB(b, h) + boff + n * 2048 + k * 1024); } while (0)
; #define PG8_MMA(ai, bj, At, Bt) do { __builtin_amdgcn_s_setprio(1); _Pragma("unroll") for (int m = 0; m < 4; ++m) _Pragma("unroll") for (int n = 0; n < 2; ++n) _Pragma("unroll") for (int k = 0; k < 2; ++k) \
;         acc[ai][bj][m][n] = __builtin_amdgcn_mfma_f32_16x16x32_bf16(Bt[n][k], At[m][k], acc[ai][bj][m][n], 0, 0, 0); __builtin_amdgcn_s_setprio(0); } while (0)
; #define PG8_WAIT_V(n) asm volatile("s_waitcnt vmcnt(" #n ")" ::: "memory")
; #define PG8_WAIT_L(n) asm volatile("s_waitcnt lgkmcnt(" #n ")" ::: "memory")
; #define PG8_BAR __builtin_amdgcn_s_barrier()
; #define PG8_SCHED __builtin_amdgcn_sched_barrier(0)
; template <class Epi, class Sched, bool ALIGN_EPI = false, bool SP2 = false>
; __device__ __forceinline__ void gemm_phase(PG8_LAS unsigned char* lds, const Gemm g, const Sched& S, const Epi& E) {
;     ...
;             PG8_LDA(At, 0, 1); PG8_STAGE(PG8_SB(0, 0), b2, voffB); PG8_STAGE(PG8_SB(0, 1), b2 + hstep, voffB); PG8_STAGE(PG8_SA(0, 0), a2, voffA);
;             PG8_WAIT_V(8); PG8_WAIT_L(0); PG8_BAR; PG8_MMA(1, 0, At, B0); PG8_MMA(1, 1, At, B1); PG8_BAR; PG8_SCHED;
;             PG8_LDB(B0, 1, 0); PG8_LDB(B1, 1, 1); PG8_SCHED; PG8_LDA(At, 1, 0); PG8_STAGE(PG8_SA(0, 1), a2 + hstep, voffA);
	s_add_i32 s58, s58, s31
	v_lshl_add_u64 v[194:195], s[56:57], 0, v[2:3]
	s_mov_b32 m0, s58
	ds_read_b128 v[178:181], v149 offset:16384
	ds_read_b128 v[182:185], v149 offset:17408
	ds_read_b128 v[186:189], v149 offset:18432
	ds_read_b128 v[190:193], v149 offset:19456
	ds_read_b128 v[204:207], v149 offset:20480
	ds_read_b128 v[220:223], v149 offset:21504
	ds_read_b128 v[224:227], v149 offset:22528
	ds_read_b128 v[228:231], v149 offset:23552
	global_load_lds_dwordx4 v[194:195], off
	s_add_i32 m0, s58, 0x2000
	v_lshl_add_u64 v[196:197], s[56:57], 0, v[132:133]
	s_add_u32 s56, s56, s10
	s_addc_u32 s57, s57, 0
	s_add_i32 s58, s59, s31
	global_load_lds_dwordx4 v[196:197], off
	v_lshl_add_u64 v[232:233], s[56:57], 0, v[2:3]
	s_mov_b32 m0, s58
	v_lshl_add_u64 v[234:235], s[56:57], 0, v[132:133]
	global_load_lds_dwordx4 v[232:233], off
	s_add_i32 m0, s58, 0x2000
	v_lshl_add_u64 v[236:237], s[28:29], 0, v[136:137]
	global_load_lds_dwordx4 v[234:235], off
	s_mov_b32 m0, s34
	v_lshl_add_u64 v[238:239], s[28:29], 0, v[134:135]
	global_load_lds_dwordx4 v[236:237], off
	s_mov_b32 m0, s35
	s_nop 0
	global_load_lds_dwordx4 v[238:239], off
	s_waitcnt vmcnt(8)
	s_waitcnt lgkmcnt(0)
	s_barrier
	s_waitcnt lgkmcnt(0)
	v_mfma_f32_16x16x32_bf16 v[64:67], v[142:145], v[178:181], v[64:67]
	v_mfma_f32_16x16x32_bf16 v[60:63], v[154:157], v[178:181], v[60:63]
	v_mfma_f32_16x16x32_bf16 v[48:51], v[142:145], v[186:189], v[48:51]
	v_mfma_f32_16x16x32_bf16 v[44:47], v[154:157], v[186:189], v[44:47]
	v_mfma_f32_16x16x32_bf16 v[32:35], v[142:145], v[204:207], v[32:35]
	v_mfma_f32_16x16x32_bf16 v[28:31], v[154:157], v[204:207], v[28:31]
	v_mfma_f32_16x16x32_bf16 v[16:19], v[142:145], v[224:227], v[16:19]
	v_mfma_f32_16x16x32_bf16 v[12:15], v[154:157], v[224:227], v[12:15]
	v_mfma_f32_16x16x32_bf16 v[64:67], v[150:153], v[182:185], v[64:67]
	v_mfma_f32_16x16x32_bf16 v[60:63], v[158:161], v[182:185], v[60:63]
	v_mfma_f32_16x16x32_bf16 v[48:51], v[150:153], v[190:193], v[48:51]
	v_mfma_f32_16x16x32_bf16 v[44:47], v[158:161], v[190:193], v[44:47]
	v_mfma_f32_16x16x32_bf16 v[32:35], v[150:153], v[220:223], v[32:35]
	v_mfma_f32_16x16x32_bf16 v[28:31], v[158:161], v[220:223], v[28:31]
	v_mfma_f32_16x16x32_bf16 v[16:19], v[150:153], v[228:231], v[16:19]
	v_mfma_f32_16x16x32_bf16 v[12:15], v[158:161], v[228:231], v[12:15]
	v_mfma_f32_16x16x32_bf16 v[56:59], v[162:165], v[178:181], v[56:59]
	v_mfma_f32_16x16x32_bf16 v[52:55], v[170:173], v[178:181], v[52:55]
	v_mfma_f32_16x16x32_bf16 v[40:43], v[162:165], v[186:189], v[40:43]
	v_mfma_f32_16x16x32_bf16 v[36:39], v[170:173], v[186:189], v[36:39]
	v_mfma_f32_16x16x32_bf16 v[24:27], v[162:165], v[204:207], v[24:27]
	v_mfma_f32_16x16x32_bf16 v[20:23], v[170:173], v[204:207], v[20:23]
	v_mfma_f32_16x16x32_bf16 v[8:11], v[162:165], v[224:227], v[8:11]
	v_mfma_f32_16x16x32_bf16 v[4:7], v[170:173], v[224:227], v[4:7]
	v_mfma_f32_16x16x32_bf16 v[56:59], v[166:169], v[182:185], v[56:59]
	v_mfma_f32_16x16x32_bf16 v[52:55], v[174:177], v[182:185], v[52:55]
	v_mfma_f32_16x16x32_bf16 v[40:43], v[166:169], v[190:193], v[40:43]
	v_mfma_f32_16x16x32_bf16 v[36:39], v[174:177], v[190:193], v[36:39]
	v_mfma_f32_16x16x32_bf16 v[24:27], v[166:169], v[220:223], v[24:27]
	v_mfma_f32_16x16x32_bf16 v[20:23], v[174:177], v[220:223], v[20:23]
	v_mfma_f32_16x16x32_bf16 v[8:11], v[166:169], v[228:231], v[8:11]
	v_mfma_f32_16x16x32_bf16 v[4:7], v[174:177], v[228:231], v[4:7]
	s_barrier
	s_add_i32 s56, 0, 0x18000
	s_add_i32 s57, 0, 0x1c000
	v_add_u32_e32 v158, s56, v147
	v_add_u32_e32 v174, s57, v147
	ds_read_b128 v[142:145], v158
	ds_read_b128 v[150:153], v158 offset:1024
	ds_read_b128 v[154:157], v158 offset:2048
	ds_read_b128 v[158:161], v158 offset:3072
	ds_read_b128 v[162:165], v174
	ds_read_b128 v[166:169], v174 offset:1024
	ds_read_b128 v[170:173], v174 offset:2048
	ds_read_b128 v[174:177], v174 offset:3072
	s_add_u32 s28, s28, s10
	s_addc_u32 s29, s29, 0
	s_mov_b32 m0, s41
	v_lshl_add_u64 v[240:241], s[28:29], 0, v[136:137]
	ds_read_b128 v[178:181], v149 offset:32768
	ds_read_b128 v[182:185], v149 offset:33792
	ds_read_b128 v[186:189], v149 offset:34816
	ds_read_b128 v[190:193], v149 offset:35840
	ds_read_b128 v[204:207], v149 offset:36864
	ds_read_b128 v[220:223], v149 offset:37888
	ds_read_b128 v[224:227], v149 offset:38912
	ds_read_b128 v[228:231], v149 offset:39936
	global_load_lds_dwordx4 v[240:241], off
	v_lshl_add_u64 v[240:241], s[28:29], 0, v[134:135]
	s_mov_b32 m0, s42
	s_nop 0
	global_load_lds_dwordx4 v[240:241], off
	s_waitcnt vmcnt(8)
	s_waitcnt lgkmcnt(0)
	s_barrier
; #define PG8_STAGE(bufoff, gbase, voff) do { _Pragma("unroll") for (int _i = 0; _i < 2; ++_i) \
;         __builtin_amdgcn_global_load_lds((const unsigned*)((const char*)(gbase) + (voff)[_i]), (PG8_LAS unsigned*)(lds + (bufoff) + ldsw + _i * 8192), 16, 0, 0); } while (0)
; #define PG8_LDA(dst, b, h) do { _Pragma("unroll") for (int m = 0; m < 4; ++m) _Pragma("unroll") for (int k = 0; k < 2; ++k) dst[m][k] = *(const PG8_LAS bf16x8*)(lds + PG8_SA(b, h) + aoff + m * 2048 + k * 1024); } while (0)
; #define PG8_MMA(ai, bj, At, Bt) do { __builtin_amdgcn_s_setprio(1); _Pragma("unroll") for (int m = 0; m < 4; ++m) _Pragma("unroll") for (int n = 0; n < 2; ++n) _Pragma("unroll") for (int k = 0; k < 2; ++k) \
;         acc[ai][bj][m][n] = __builtin_amdgcn_mfma_f32_16x16x32_bf16(Bt[n][k], At[m][k], acc[ai][bj][m][n], 0, 0, 0); __builtin_amdgcn_s_setprio(0); } while (0)
; #define PG8_WAIT_V(n) asm volatile("s_waitcnt vmcnt(" #n ")" ::: "memory")
; #define PG8_WAIT_L(n) asm volatile("s_waitcnt lgkmcnt(" #n ")" ::: "memory")
; #define PG8_BAR __builtin_amdgcn_s_barrier()
; #define PG8_SCHED __builtin_amdgcn_sched_barrier(0)
; template <class Epi, class Sched, bool ALIGN_EPI = false, bool SP2 = false>
; __device__ __forceinline__ void gemm_phase(PG8_LAS unsigned char* lds, const Gemm g, const Sched& S, const Epi& E) {
;     ...
;             PG8_WAIT_V(8); PG8_WAIT_L(0); PG8_BAR; PG8_MMA(0, 0, At, B0); PG8_MMA(0, 1, At, B1); PG8_BAR; PG8_SCHED;
;             PG8_LDA(At, 1, 1); PG8_STAGE(PG8_SB(1, 0), b3, voffB); PG8_STAGE(PG8_SB(1, 1), b3 + hstep, voffB); PG8_STAGE(PG8_SA(1, 0), a3, voffA);
;             PG8_WAIT_V(8); PG8_WAIT_L(0); PG8_BAR; PG8_MMA(1, 0, At, B0); PG8_MMA(1, 1, At, B1); PG8_BAR; PG8_SCHED;
;     ...
;         if constexpr (ALIGN_EPI) { if (wr == 0) PG8_BAR; }
	s_waitcnt lgkmcnt(0)
	v_mfma_f32_16x16x32_bf16 v[128:131], v[142:145], v[178:181], v[128:131]
	v_mfma_f32_16x16x32_bf16 v[124:127], v[154:157], v[178:181], v[124:127]
	v_mfma_f32_16x16x32_bf16 v[112:115], v[142:145], v[186:189], v[112:115]
	v_mfma_f32_16x16x32_bf16 v[108:111], v[154:157], v[186:189], v[108:111]
	v_mfma_f32_16x16x32_bf16 v[96:99], v[142:145], v[204:207], v[96:99]
	v_mfma_f32_16x16x32_bf16 v[92:95], v[154:157], v[204:207], v[92:95]
	v_mfma_f32_16x16x32_bf16 v[80:83], v[142:145], v[224:227], v[80:83]
	v_mfma_f32_16x16x32_bf16 v[76:79], v[154:157], v[224:227], v[76:79]
	v_mfma_f32_16x16x32_bf16 v[128:131], v[150:153], v[182:185], v[128:131]
	v_mfma_f32_16x16x32_bf16 v[124:127], v[158:161], v[182:185], v[124:127]
	v_mfma_f32_16x16x32_bf16 v[112:115], v[150:153], v[190:193], v[112:115]
	v_mfma_f32_16x16x32_bf16 v[108:111], v[158:161], v[190:193], v[108:111]
	v_mfma_f32_16x16x32_bf16 v[96:99], v[150:153], v[220:223], v[96:99]
	v_mfma_f32_16x16x32_bf16 v[92:95], v[158:161], v[220:223], v[92:95]
	v_mfma_f32_16x16x32_bf16 v[80:83], v[150:153], v[228:231], v[80:83]
	v_mfma_f32_16x16x32_bf16 v[76:79], v[158:161], v[228:231], v[76:79]
	v_mfma_f32_16x16x32_bf16 v[120:123], v[162:165], v[178:181], v[120:123]
	v_mfma_f32_16x16x32_bf16 v[116:119], v[170:173], v[178:181], v[116:119]
	v_mfma_f32_16x16x32_bf16 v[104:107], v[162:165], v[186:189], v[104:107]
	v_mfma_f32_16x16x32_bf16 v[100:103], v[170:173], v[186:189], v[100:103]
	v_mfma_f32_16x16x32_bf16 v[88:91], v[162:165], v[204:207], v[88:91]
	v_mfma_f32_16x16x32_bf16 v[84:87], v[170:173], v[204:207], v[84:87]
	v_mfma_f32_16x16x32_bf16 v[72:75], v[162:165], v[224:227], v[72:75]
	v_mfma_f32_16x16x32_bf16 v[68:71], v[170:173], v[224:227], v[68:71]
	v_mfma_f32_16x16x32_bf16 v[120:123], v[166:169], v[182:185], v[120:123]
	v_mfma_f32_16x16x32_bf16 v[116:119], v[174:177], v[182:185], v[116:119]
	v_mfma_f32_16x16x32_bf16 v[104:107], v[166:169], v[190:193], v[104:107]
	v_mfma_f32_16x16x32_bf16 v[100:103], v[174:177], v[190:193], v[100:103]
	v_mfma_f32_16x16x32_bf16 v[88:91], v[166:169], v[220:223], v[88:91]
	v_mfma_f32_16x16x32_bf16 v[84:87], v[174:177], v[220:223], v[84:87]
	v_mfma_f32_16x16x32_bf16 v[72:75], v[166:169], v[228:231], v[72:75]
	v_mfma_f32_16x16x32_bf16 v[68:71], v[174:177], v[228:231], v[68:71]
	s_barrier
	s_add_i32 s28, s56, s31
	v_lshl_add_u64 v[194:195], v[194:195], 0, s[92:93]
	s_mov_b32 m0, s28
	ds_read_b128 v[178:181], v149 offset:49152
	ds_read_b128 v[182:185], v149 offset:50176
	ds_read_b128 v[186:189], v149 offset:51200
	ds_read_b128 v[190:193], v149 offset:52224
	ds_read_b128 v[204:207], v149 offset:53248
	ds_read_b128 v[220:223], v149 offset:54272
	ds_read_b128 v[224:227], v149 offset:55296
	ds_read_b128 v[228:231], v149 offset:56320
	global_load_lds_dwordx4 v[194:195], off
	v_lshl_add_u64 v[194:195], v[196:197], 0, s[92:93]
	s_add_i32 m0, s28, 0x2000
	s_add_i32 s28, s57, s31
	global_load_lds_dwordx4 v[194:195], off
	v_lshl_add_u64 v[194:195], v[232:233], 0, s[92:93]
	s_mov_b32 m0, s28
	s_nop 0
	global_load_lds_dwordx4 v[194:195], off
	v_lshl_add_u64 v[194:195], v[234:235], 0, s[92:93]
	s_add_i32 m0, s28, 0x2000
	s_nop 0
	global_load_lds_dwordx4 v[194:195], off
	v_lshl_add_u64 v[194:195], v[236:237], 0, s[92:93]
	s_mov_b32 m0, s45
	s_nop 0
	global_load_lds_dwordx4 v[194:195], off
	v_lshl_add_u64 v[194:195], v[238:239], 0, s[92:93]
	s_mov_b32 m0, s46
	s_nop 0
	global_load_lds_dwordx4 v[194:195], off
	s_waitcnt vmcnt(8)
	s_waitcnt lgkmcnt(0)
	s_barrier
	s_waitcnt lgkmcnt(0)
	v_mfma_f32_16x16x32_bf16 v[64:67], v[142:145], v[178:181], v[64:67]
	v_mfma_f32_16x16x32_bf16 v[60:63], v[154:157], v[178:181], v[60:63]
	v_mfma_f32_16x16x32_bf16 v[48:51], v[142:145], v[186:189], v[48:51]
	v_mfma_f32_16x16x32_bf16 v[44:47], v[154:157], v[186:189], v[44:47]
	v_mfma_f32_16x16x32_bf16 v[32:35], v[142:145], v[204:207], v[32:35]
	v_mfma_f32_16x16x32_bf16 v[28:31], v[154:157], v[204:207], v[28:31]
	v_mfma_f32_16x16x32_bf16 v[16:19], v[142:145], v[224:227], v[16:19]
	v_mfma_f32_16x16x32_bf16 v[12:15], v[154:157], v[224:227], v[12:15]
	v_mfma_f32_16x16x32_bf16 v[64:67], v[150:153], v[182:185], v[64:67]
	v_mfma_f32_16x16x32_bf16 v[60:63], v[158:161], v[182:185], v[60:63]
	v_mfma_f32_16x16x32_bf16 v[48:51], v[150:153], v[190:193], v[48:51]
	v_mfma_f32_16x16x32_bf16 v[44:47], v[158:161], v[190:193], v[44:47]
	v_mfma_f32_16x16x32_bf16 v[32:35], v[150:153], v[220:223], v[32:35]
	v_mfma_f32_16x16x32_bf16 v[28:31], v[158:161], v[220:223], v[28:31]
	v_mfma_f32_16x16x32_bf16 v[16:19], v[150:153], v[228:231], v[16:19]
	v_mfma_f32_16x16x32_bf16 v[12:15], v[158:161], v[228:231], v[12:15]
	v_mfma_f32_16x16x32_bf16 v[56:59], v[162:165], v[178:181], v[56:59]
	v_mfma_f32_16x16x32_bf16 v[52:55], v[170:173], v[178:181], v[52:55]
	v_mfma_f32_16x16x32_bf16 v[40:43], v[162:165], v[186:189], v[40:43]
	v_mfma_f32_16x16x32_bf16 v[36:39], v[170:173], v[186:189], v[36:39]
	v_mfma_f32_16x16x32_bf16 v[24:27], v[162:165], v[204:207], v[24:27]
	v_mfma_f32_16x16x32_bf16 v[20:23], v[170:173], v[204:207], v[20:23]
	v_mfma_f32_16x16x32_bf16 v[8:11], v[162:165], v[224:227], v[8:11]
	v_mfma_f32_16x16x32_bf16 v[4:7], v[170:173], v[224:227], v[4:7]
	v_mfma_f32_16x16x32_bf16 v[56:59], v[166:169], v[182:185], v[56:59]
	v_mfma_f32_16x16x32_bf16 v[52:55], v[174:177], v[182:185], v[52:55]
	v_mfma_f32_16x16x32_bf16 v[40:43], v[166:169], v[190:193], v[40:43]
	v_mfma_f32_16x16x32_bf16 v[36:39], v[174:177], v[190:193], v[36:39]
	v_mfma_f32_16x16x32_bf16 v[24:27], v[166:169], v[220:223], v[24:27]
	v_mfma_f32_16x16x32_bf16 v[20:23], v[174:177], v[220:223], v[20:23]
	v_mfma_f32_16x16x32_bf16 v[8:11], v[166:169], v[228:231], v[8:11]
	v_mfma_f32_16x16x32_bf16 v[4:7], v[174:177], v[228:231], v[4:7]
	s_barrier
	s_add_u32 s26, s26, 0x100
	s_addc_u32 s27, s27, 0
	s_add_u32 s33, s33, 0x100
	s_addc_u32 s54, s54, 0
	s_cmp_ge_u32 s55, s44
	s_mov_b32 s28, s55
	s_cbranch_scc0 .LBB0_638
	s_and_b64 vcc, exec, s[22:23]
	s_cbranch_vccz .LBB0_641
	s_barrier
; __device__ __forceinline__ unsigned cvt_pk_bf16(float lo, float hi) { unsigned r; asm volatile("v_cvt_pk_bf16_f32 %0, %1, %2" : "=v"(r) : "v"(lo), "v"(hi)); return r; }
;     __device__ __forceinline__ void operator()(const f32x4 (&acc)[2][2][4][2], const Unit& u, int wr, int wc, int fr, int fq) const {
;         const int row0 = u.pm * BM + wr * 64 + fr, col0 = u.pn * BM + wc * 32 + 8 * fq;
; #pragma unroll
;         for (int ai = 0; ai < 2; ++ai)
; #pragma unroll
;             for (int m = 0; m < 4; ++m) { const int row = row0 + ai * HALF + m * 16; const size_t off = (size_t)row * 1024 + col0; float part = 0.f;
; #pragma unroll
;                 for (int bj = 0; bj < 2; ++bj) { const u32x4 b = *(const u32x4*)(hb + off + bj * HALF);
;                     f32x4 v0 = acc[ai][bj][m][0], v1 = acc[ai][bj][m][1];
;                     v0[0] += __uint_as_float(b.x << 16); v0[1] += __uint_as_float(b.x & 0xffff0000u); v0[2] += __uint_as_float(b.y << 16); v0[3] += __uint_as_float(b.y & 0xffff0000u);
;                     v1[0] += __uint_as_float(b.z << 16); v1[1] += __uint_as_float(b.z & 0xffff0000u); v1[2] += __uint_as_float(b.w << 16); v1[3] += __uint_as_float(b.w & 0xffff0000u);
;                     u32x4 w; w.x = cvt_pk_bf16(v0[0], v0[1]); w.y = cvt_pk_bf16(v0[2], v0[3]); w.z = cvt_pk_bf16(v1[0], v1[1]); w.w = cvt_pk_bf16(v1[2], v1[3]);
;                     *(u32x4*)(hb + off + bj * HALF) = w;
;                     part += (v0[0] * v0[0] + v0[1] * v0[1]) + (v0[2] * v0[2] + v0[3] * v0[3]) + (v1[0] * v1[0] + v1[1] * v1[1]) + (v1[2] * v1[2] + v1[3] * v1[3]); }
;                 part += __shfl_xor(part, 16); part += __shfl_xor(part, 32);
;                 if (fq == 0) ssq[(size_t)row * 16 + u.pn * 4 + wc] = part; }
.LBB0_641:
	s_setprio 0
	v_lshl_add_u32 v144, s53, 8, v146
	v_ashrrev_i32_e32 v145, 31, v144
	v_lshl_or_b32 v142, s11, 8, v148
	v_lshlrev_b64 v[150:151], 11, v[144:145]
	v_ashrrev_i32_e32 v143, 31, v142
	v_lshl_add_u64 v[150:151], s[8:9], 0, v[150:151]
	v_lshl_add_u64 v[154:155], v[142:143], 1, v[150:151]
	global_load_dwordx4 v[150:153], v[154:155], off
	s_waitcnt vmcnt(0)
	v_lshlrev_b32_e32 v156, 16, v150
	v_and_b32_e32 v150, 0xffff0000, v150
	v_add_f32_e32 v129, v129, v150
	v_lshlrev_b32_e32 v150, 16, v151
	v_add_f32_e32 v130, v130, v150
	v_and_b32_e32 v150, 0xffff0000, v151
	v_add_f32_e32 v131, v131, v150
	v_lshlrev_b32_e32 v150, 16, v152
	v_add_f32_e32 v150, v124, v150
	v_and_b32_e32 v124, 0xffff0000, v152
	v_add_f32_e32 v151, v125, v124
	v_lshlrev_b32_e32 v124, 16, v153
	v_add_f32_e32 v152, v126, v124
	v_and_b32_e32 v124, 0xffff0000, v153
	v_add_f32_e32 v128, v128, v156
	v_add_f32_e32 v153, v127, v124
	v_cvt_pk_bf16_f32 v124, v128, v129
	v_cvt_pk_bf16_f32 v125, v130, v131
	v_cvt_pk_bf16_f32 v126, v150, v151
	v_cvt_pk_bf16_f32 v127, v152, v153
	global_store_dwordx4 v[154:155], v[124:127], off
	s_nop 1
	v_mul_f32_e32 v124, v129, v129
	v_mul_f32_e32 v125, v131, v131
	v_fmac_f32_e32 v124, v128, v128
	v_fmac_f32_e32 v125, v130, v130
	v_add_f32_e32 v124, v124, v125
	v_mul_f32_e32 v125, v151, v151
	v_fmac_f32_e32 v125, v150, v150
	v_add_f32_e32 v124, v125, v124
	v_mul_f32_e32 v125, v153, v153
	v_fmac_f32_e32 v125, v152, v152
	v_add_f32_e32 v128, v125, v124
	global_load_dwordx4 v[124:127], v[154:155], off offset:256
	s_waitcnt vmcnt(0)
	v_lshlrev_b32_e32 v129, 16, v124
	v_and_b32_e32 v124, 0xffff0000, v124
	v_add_f32_e32 v121, v121, v124
	v_lshlrev_b32_e32 v124, 16, v125
	v_add_f32_e32 v122, v122, v124
	v_and_b32_e32 v124, 0xffff0000, v125
	v_add_f32_e32 v123, v123, v124
	v_lshlrev_b32_e32 v124, 16, v126
	v_add_f32_e32 v124, v116, v124
	v_and_b32_e32 v116, 0xffff0000, v126
	v_add_f32_e32 v125, v117, v116
	v_lshlrev_b32_e32 v116, 16, v127
	v_add_f32_e32 v126, v118, v116
	v_and_b32_e32 v116, 0xffff0000, v127
	v_add_f32_e32 v120, v120, v129
	v_add_f32_e32 v127, v119, v116
	v_cvt_pk_bf16_f32 v116, v120, v121
	v_cvt_pk_bf16_f32 v117, v122, v123
	v_cvt_pk_bf16_f32 v118, v124, v125
	v_cvt_pk_bf16_f32 v119, v126, v127
	global_store_dwordx4 v[154:155], v[116:119], off offset:256
	s_nop 1
	v_mul_f32_e32 v116, v121, v121
	v_mul_f32_e32 v117, v123, v123
	v_fmac_f32_e32 v116, v120, v120
	v_fmac_f32_e32 v117, v122, v122
	v_add_f32_e32 v116, v116, v117
	v_mul_f32_e32 v117, v125, v125
	v_fmac_f32_e32 v117, v124, v124
	v_add_f32_e32 v116, v117, v116
	v_mul_f32_e32 v117, v127, v127
	v_fmac_f32_e32 v117, v126, v126
	v_and_b32_e32 v118, 64, v214
	v_add_f32_e32 v116, v117, v116
	v_xor_b32_e32 v117, 16, v214
	v_add_u32_e32 v118, 64, v118
	v_cmp_lt_i32_e32 vcc, v117, v118
	v_add_f32_e32 v116, v128, v116
	s_nop 0
	v_cndmask_b32_e32 v117, v214, v117, vcc
	v_lshlrev_b32_e32 v120, 2, v117
	ds_bpermute_b32 v117, v120, v116
	s_waitcnt lgkmcnt(0)
	v_add_f32_e32 v116, v116, v117
	v_xor_b32_e32 v117, 32, v214
	v_cmp_lt_i32_e32 vcc, v117, v118
	s_nop 1
	v_cndmask_b32_e32 v117, v214, v117, vcc
	v_lshlrev_b32_e32 v121, 2, v117
	ds_bpermute_b32 v117, v121, v116
	s_and_saveexec_b64 s[26:27], s[2:3]
	s_cbranch_execz .LBB0_643
	s_waitcnt lgkmcnt(0)
	v_add_f32_e32 v118, v116, v117
	s_lshl_b32 s28, s11, 2
	v_lshlrev_b64 v[116:117], 6, v[144:145]
	s_ashr_i32 s29, s28, 31
	v_lshl_add_u64 v[116:117], s[20:21], 0, v[116:117]
	v_lshl_add_u64 v[116:117], s[28:29], 2, v[116:117]
	s_lshl_b32 s84, s43, 2
	v_lshl_add_u64 v[116:117], v[116:117], 0, s[84:85]
	global_store_dword v[116:117], v118, off

; #define PG8_STAGE(bufoff, gbase, voff) do { _Pragma("unroll") for (int _i = 0; _i < 2; ++_i) \
;         __builtin_amdgcn_global_load_lds((const unsigned*)((const char*)(gbase) + (voff)[_i]), (PG8_LAS unsigned*)(lds + (bufoff) + ldsw + _i * 8192), 16, 0, 0); } while (0)
; #define PG8_LDA(dst, b, h) do { _Pragma("unroll") for (int m = 0; m < 4; ++m) _Pragma("unroll") for (int k = 0; k < 2; ++k) dst[m][k] = *(const PG8_LAS bf16x8*)(lds + PG8_SA(b, h) + aoff + m * 2048 + k * 1024); } while (0)
; #define PG8_LDB(dst, b, h) do { _Pragma("unroll") for (int n = 0; n < 2; ++n) _Pragma("unroll") for (int k = 0; k < 2; ++k) dst[n][k] = *(const PG8_LAS bf16x8*)(lds + PG8_SB(b, h) + boff + n * 2048 + k * 1024); } while (0)
; #define PG8_WAIT_V(n) asm volatile("s_waitcnt vmcnt(" #n ")" ::: "memory")
; #define PG8_WAIT_L(n) asm volatile("s_waitcnt lgkmcnt(" #n ")" ::: "memory")
; #define PG8_BAR __builtin_amdgcn_s_barrier()
; #define PG8_SCHED __builtin_amdgcn_sched_barrier(0)
; template <class Epi, class Sched, bool ALIGN_EPI = false, bool SP2 = false>
; __device__ __forceinline__ void gemm_phase(PG8_LAS unsigned char* lds, const Gemm g, const Sched& S, const Epi& E) {
;     ...
;         const char* nA = has_next ? (const char*)g.A + (size_t)nxt.pm * tstep : cA; const char* nB = has_next ? (const char*)g.Bt + (size_t)nxt.pn * tstep : cB;
;         for (int t = 0; t < nt; t += 2) {
;             const bool last = (t == nt - 2);
;             const char* a1 = cA + (size_t)(t + 1) * kstep;
;             const char* a2 = last ? nA : cA + (size_t)(t + 2) * kstep; const char* b2 = last ? nB : cB + (size_t)(t + 2) * kstep;
;             const char* a3 = a2 + kstep; const char* b3 = b2 + kstep;
;             if (last && has_next) S.a_ready(nxt);
;             if constexpr (SP2) {
;             PG8_LDB(B0, 0, 0); PG8_LDB(B1, 0, 1); PG8_SCHED; PG8_LDA(At, 0, 0); PG8_STAGE(PG8_SA(1, 1), a1 + hstep, voffA);
;             PG8_WAIT_V(8); PG8_WAIT_L(0); PG8_BAR; PG8_MMA(0, 0, At, B0); PG8_MMA(0, 1, At, B1); PG8_BAR; PG8_SCHED;
;     ...
;         for (int a = 0; a < 2; ++a)
; #pragma unroll
;             for (int b = 0; b < 2; ++b)
; #pragma unroll
;                 for (int m = 0; m < 4; ++m)
; #pragma unroll
;                     for (int n = 0; n < 2; ++n) acc[a][b][m][n] = (f32x4){0.f, 0.f, 0.f, 0.f};
.LBB0_684:
	s_ashr_i32 s35, s34, 31
	s_lshl_b64 s[36:37], s[34:35], 19
	s_add_u32 s36, s24, s36
	s_addc_u32 s37, s25, s37
	s_and_b64 s[38:39], s[2:3], exec
	s_cselect_b32 s33, s37, s43
	s_cselect_b32 s35, s36, s42
	s_ashr_i32 s31, s30, 31
	s_lshl_b64 s[38:39], s[30:31], 19
	s_add_u32 s38, s20, s38
	s_addc_u32 s39, s21, s39
	s_and_b64 s[46:47], s[2:3], exec
	s_cselect_b32 s31, s39, s45
	s_cselect_b32 s65, s38, s44
	s_add_u32 s42, s42, 0x40080
	s_addc_u32 s43, s43, 0
	s_add_u32 s66, s44, 0x100
	s_addc_u32 s67, s45, 0
	s_mov_b32 s68, -2
	v_mov_b64_e32 v[4:5], 0
	v_mov_b64_e32 v[6:7], 0
	v_mov_b64_e32 v[8:9], 0
	v_mov_b64_e32 v[10:11], 0
	v_mov_b64_e32 v[12:13], 0
	v_mov_b64_e32 v[14:15], 0
	v_mov_b64_e32 v[16:17], 0
	v_mov_b64_e32 v[18:19], 0
	v_mov_b64_e32 v[20:21], 0
	v_mov_b64_e32 v[22:23], 0
	v_mov_b64_e32 v[24:25], 0
	v_mov_b64_e32 v[26:27], 0
	v_mov_b64_e32 v[28:29], 0
	v_mov_b64_e32 v[30:31], 0
	v_mov_b64_e32 v[32:33], 0
	v_mov_b64_e32 v[34:35], 0
	v_mov_b64_e32 v[36:37], 0
	v_mov_b64_e32 v[38:39], 0
	v_mov_b64_e32 v[40:41], 0
	v_mov_b64_e32 v[42:43], 0
	v_mov_b64_e32 v[44:45], 0
	v_mov_b64_e32 v[46:47], 0
	v_mov_b64_e32 v[48:49], 0
	v_mov_b64_e32 v[50:51], 0
	v_mov_b64_e32 v[52:53], 0
	v_mov_b64_e32 v[54:55], 0
	v_mov_b64_e32 v[56:57], 0
	v_mov_b64_e32 v[58:59], 0
	v_mov_b64_e32 v[60:61], 0
	v_mov_b64_e32 v[62:63], 0
	v_mov_b64_e32 v[64:65], 0
	v_mov_b64_e32 v[66:67], 0
	v_mov_b64_e32 v[68:69], 0
	v_mov_b64_e32 v[70:71], 0
	v_mov_b64_e32 v[72:73], 0
	v_mov_b64_e32 v[74:75], 0
	v_mov_b64_e32 v[76:77], 0
	v_mov_b64_e32 v[78:79], 0
	v_mov_b64_e32 v[80:81], 0
	v_mov_b64_e32 v[82:83], 0
	v_mov_b64_e32 v[84:85], 0
	v_mov_b64_e32 v[86:87], 0
	v_mov_b64_e32 v[88:89], 0
	v_mov_b64_e32 v[90:91], 0
	v_mov_b64_e32 v[92:93], 0
	v_mov_b64_e32 v[94:95], 0
	v_mov_b64_e32 v[96:97], 0
	v_mov_b64_e32 v[98:99], 0
	v_mov_b64_e32 v[100:101], 0
	v_mov_b64_e32 v[102:103], 0
	v_mov_b64_e32 v[104:105], 0
	v_mov_b64_e32 v[106:107], 0
	v_mov_b64_e32 v[108:109], 0
	v_mov_b64_e32 v[110:111], 0
	v_mov_b64_e32 v[112:113], 0
	v_mov_b64_e32 v[114:115], 0
	v_mov_b64_e32 v[116:117], 0
	v_mov_b64_e32 v[118:119], 0
	v_mov_b64_e32 v[120:121], 0
	v_mov_b64_e32 v[122:123], 0
	v_mov_b64_e32 v[124:125], 0
	v_mov_b64_e32 v[126:127], 0
	v_mov_b64_e32 v[128:129], 0
	v_mov_b64_e32 v[130:131], 0
	v_readfirstlane_b32 s89, v0
	s_nop 3
	s_lshr_b32 s89, s89, 6
	s_cmp_lt_u32 s89, 4
	s_cbranch_scc0 .Lprio_done2
	s_setprio 1
.Lprio_done2:
.LBB0_685:
	s_add_u32 s44, s42, 0xfffc0080
	s_addc_u32 s45, s43, -1
	s_add_i32 s69, 0, 0x10000
	s_cmp_eq_u32 s68, 12
	s_cselect_b32 s47, s33, s45
	s_cselect_b32 s46, s35, s44
	s_cselect_b32 s45, s31, s67
	s_cselect_b32 s44, s65, s66
	s_add_i32 s73, 0, 0x14000
	v_add_u32_e32 v158, s69, v147
	v_add_u32_e32 v174, s73, v147
	ds_read_b128 v[142:145], v158
	ds_read_b128 v[150:153], v158 offset:1024
	ds_read_b128 v[154:157], v158 offset:2048
	ds_read_b128 v[158:161], v158 offset:3072
	ds_read_b128 v[162:165], v174
	ds_read_b128 v[166:169], v174 offset:1024
	ds_read_b128 v[170:173], v174 offset:2048
	ds_read_b128 v[174:177], v174 offset:3072
	v_lshl_add_u64 v[194:195], s[42:43], 0, v[138:139]
	s_add_i32 m0, s58, 0xc000
	ds_read_b128 v[178:181], v149
	ds_read_b128 v[182:185], v149 offset:1024
	ds_read_b128 v[186:189], v149 offset:2048
	ds_read_b128 v[190:193], v149 offset:3072
	ds_read_b128 v[204:207], v149 offset:4096
	ds_read_b128 v[220:223], v149 offset:5120
	ds_read_b128 v[224:227], v149 offset:6144
	ds_read_b128 v[228:231], v149 offset:7168
	global_load_lds_dwordx4 v[194:195], off
	v_lshl_add_u64 v[194:195], s[42:43], 0, v[140:141]
	s_add_i32 m0, s58, 0xe000
	s_nop 0
	global_load_lds_dwordx4 v[194:195], off
	s_waitcnt vmcnt(8)
	s_waitcnt lgkmcnt(0)
	s_barrier
	s_waitcnt lgkmcnt(0)
	v_mfma_f32_16x16x32_bf16 v[128:131], v[142:145], v[178:181], v[128:131]
	v_mfma_f32_16x16x32_bf16 v[124:127], v[154:157], v[178:181], v[124:127]
	v_mfma_f32_16x16x32_bf16 v[112:115], v[142:145], v[186:189], v[112:115]
	v_mfma_f32_16x16x32_bf16 v[108:111], v[154:157], v[186:189], v[108:111]
	v_mfma_f32_16x16x32_bf16 v[96:99], v[142:145], v[204:207], v[96:99]
	v_mfma_f32_16x16x32_bf16 v[92:95], v[154:157], v[204:207], v[92:95]
	v_mfma_f32_16x16x32_bf16 v[80:83], v[142:145], v[224:227], v[80:83]
	v_mfma_f32_16x16x32_bf16 v[76:79], v[154:157], v[224:227], v[76:79]
	v_mfma_f32_16x16x32_bf16 v[128:131], v[150:153], v[182:185], v[128:131]
	v_mfma_f32_16x16x32_bf16 v[124:127], v[158:161], v[182:185], v[124:127]
	v_mfma_f32_16x16x32_bf16 v[112:115], v[150:153], v[190:193], v[112:115]
	v_mfma_f32_16x16x32_bf16 v[108:111], v[158:161], v[190:193], v[108:111]
	v_mfma_f32_16x16x32_bf16 v[96:99], v[150:153], v[220:223], v[96:99]
	v_mfma_f32_16x16x32_bf16 v[92:95], v[158:161], v[220:223], v[92:95]
	v_mfma_f32_16x16x32_bf16 v[80:83], v[150:153], v[228:231], v[80:83]
	v_mfma_f32_16x16x32_bf16 v[76:79], v[158:161], v[228:231], v[76:79]
	v_mfma_f32_16x16x32_bf16 v[120:123], v[162:165], v[178:181], v[120:123]
	v_mfma_f32_16x16x32_bf16 v[116:119], v[170:173], v[178:181], v[116:119]
	v_mfma_f32_16x16x32_bf16 v[104:107], v[162:165], v[186:189], v[104:107]
	v_mfma_f32_16x16x32_bf16 v[100:103], v[170:173], v[186:189], v[100:103]
	v_mfma_f32_16x16x32_bf16 v[88:91], v[162:165], v[204:207], v[88:91]
	v_mfma_f32_16x16x32_bf16 v[84:87], v[170:173], v[204:207], v[84:87]
	v_mfma_f32_16x16x32_bf16 v[72:75], v[162:165], v[224:227], v[72:75]
	v_mfma_f32_16x16x32_bf16 v[68:71], v[170:173], v[224:227], v[68:71]
	v_mfma_f32_16x16x32_bf16 v[120:123], v[166:169], v[182:185], v[120:123]
	v_mfma_f32_16x16x32_bf16 v[116:119], v[174:177], v[182:185], v[116:119]
	v_mfma_f32_16x16x32_bf16 v[104:107], v[166:169], v[190:193], v[104:107]
	v_mfma_f32_16x16x32_bf16 v[100:103], v[174:177], v[190:193], v[100:103]
	v_mfma_f32_16x16x32_bf16 v[88:91], v[166:169], v[220:223], v[88:91]
	v_mfma_f32_16x16x32_bf16 v[84:87], v[174:177], v[220:223], v[84:87]
	v_mfma_f32_16x16x32_bf16 v[72:75], v[166:169], v[228:231], v[72:75]
	v_mfma_f32_16x16x32_bf16 v[68:71], v[174:177], v[228:231], v[68:71]
	s_barrier
; #define PG8_STAGE(bufoff, gbase, voff) do { _Pragma("unroll") for (int _i = 0; _i < 2; ++_i) \
;         __builtin_amdgcn_global_load_lds((const unsigned*)((const char*)(gbase) + (voff)[_i]), (PG8_LAS unsigned*)(lds + (bufoff) + ldsw + _i * 8192), 16, 0, 0); } while (0)
; #define PG8_LDA(dst, b, h) do { _Pragma("unroll") for (int m = 0; m < 4; ++m) _Pragma("unroll") for (int k = 0; k < 2; ++k) dst[m][k] = *(const PG8_LAS bf16x8*)(lds + PG8_SA(b, h) + aoff + m * 2048 + k * 1024); } while (0)
; #define PG8_LDB(dst, b, h) do { _Pragma("unroll") for (int n = 0; n < 2; ++n) _Pragma("unroll") for (int k = 0; k < 2; ++k) dst[n][k] = *(const PG8_LAS bf16x8*)(lds + PG8_SB(b, h) + boff + n * 2048 + k * 1024); } while (0)
; #define PG8_MMA(ai, bj, At, Bt) do { __builtin_amdgcn_s_setprio(1); _Pragma("unroll") for (int m = 0; m < 4; ++m) _Pragma("unroll") for (int n = 0; n < 2; ++n) _Pragma("unroll") for (int k = 0; k < 2; ++k) \
;         acc[ai][bj][m][n] = __builtin_amdgcn_mfma_f32_16x16x32_bf16(Bt[n][k], At[m][k], acc[ai][bj][m][n], 0, 0, 0); __builtin_amdgcn_s_setprio(0); } while (0)
; #define PG8_WAIT_V(n) asm volatile("s_waitcnt vmcnt(" #n ")" ::: "memory")
; #define PG8_WAIT_L(n) asm volatile("s_waitcnt lgkmcnt(" #n ")" ::: "memory")
; #define PG8_BAR __builtin_amdgcn_s_barrier()
; #define PG8_SCHED __builtin_amdgcn_sched_barrier(0)
; template <class Epi, class Sched, bool ALIGN_EPI = false, bool SP2 = false>
; __device__ __forceinline__ void gemm_phase(PG8_LAS unsigned char* lds, const Gemm g, const Sched& S, const Epi& E) {
;     ...
;             PG8_LDA(At, 0, 1); PG8_STAGE(PG8_SB(0, 0), b2, voffB); PG8_STAGE(PG8_SB(0, 1), b2 + hstep, voffB); PG8_STAGE(PG8_SA(0, 0), a2, voffA);
;             PG8_WAIT_V(8); PG8_WAIT_L(0); PG8_BAR; PG8_MMA(1, 0, At, B0); PG8_MMA(1, 1, At, B1); PG8_BAR; PG8_SCHED;
;             PG8_LDB(B0, 1, 0); PG8_LDB(B1, 1, 1); PG8_SCHED; PG8_LDA(At, 1, 0); PG8_STAGE(PG8_SA(0, 1), a2 + hstep, voffA);
	s_add_i32 s69, s69, s56
	v_lshl_add_u64 v[194:195], s[44:45], 0, v[2:3]
	s_mov_b32 m0, s69
	ds_read_b128 v[178:181], v149 offset:16384
	ds_read_b128 v[182:185], v149 offset:17408
	ds_read_b128 v[186:189], v149 offset:18432
	ds_read_b128 v[190:193], v149 offset:19456
	ds_read_b128 v[204:207], v149 offset:20480
	ds_read_b128 v[220:223], v149 offset:21504
	ds_read_b128 v[224:227], v149 offset:22528
	ds_read_b128 v[228:231], v149 offset:23552
	global_load_lds_dwordx4 v[194:195], off
	s_add_i32 m0, s69, 0x2000
	s_add_u32 s70, s44, 0x40000
	v_lshl_add_u64 v[196:197], s[44:45], 0, v[136:137]
	s_addc_u32 s71, s45, 0
	s_add_i32 s69, s73, s56
	global_load_lds_dwordx4 v[196:197], off
	v_lshl_add_u64 v[232:233], s[70:71], 0, v[2:3]
	s_mov_b32 m0, s69
	v_lshl_add_u64 v[234:235], s[46:47], 0, v[134:135]
	global_load_lds_dwordx4 v[232:233], off
	v_lshl_add_u64 v[232:233], s[70:71], 0, v[136:137]
	s_add_i32 m0, s69, 0x2000
	s_nop 0
	global_load_lds_dwordx4 v[232:233], off
	v_lshl_add_u64 v[232:233], s[46:47], 0, v[132:133]
	s_mov_b32 m0, s58
	s_nop 0
	global_load_lds_dwordx4 v[232:233], off
	s_mov_b32 m0, s59
	s_nop 0
	global_load_lds_dwordx4 v[234:235], off
	s_waitcnt vmcnt(8)
	s_waitcnt lgkmcnt(0)
	s_barrier
	s_waitcnt lgkmcnt(0)
	v_mfma_f32_16x16x32_bf16 v[64:67], v[142:145], v[178:181], v[64:67]
	v_mfma_f32_16x16x32_bf16 v[60:63], v[154:157], v[178:181], v[60:63]
	v_mfma_f32_16x16x32_bf16 v[48:51], v[142:145], v[186:189], v[48:51]
	v_mfma_f32_16x16x32_bf16 v[44:47], v[154:157], v[186:189], v[44:47]
	v_mfma_f32_16x16x32_bf16 v[32:35], v[142:145], v[204:207], v[32:35]
	v_mfma_f32_16x16x32_bf16 v[28:31], v[154:157], v[204:207], v[28:31]
	v_mfma_f32_16x16x32_bf16 v[16:19], v[142:145], v[224:227], v[16:19]
	v_mfma_f32_16x16x32_bf16 v[12:15], v[154:157], v[224:227], v[12:15]
	v_mfma_f32_16x16x32_bf16 v[64:67], v[150:153], v[182:185], v[64:67]
	v_mfma_f32_16x16x32_bf16 v[60:63], v[158:161], v[182:185], v[60:63]
	v_mfma_f32_16x16x32_bf16 v[48:51], v[150:153], v[190:193], v[48:51]
	v_mfma_f32_16x16x32_bf16 v[44:47], v[158:161], v[190:193], v[44:47]
	v_mfma_f32_16x16x32_bf16 v[32:35], v[150:153], v[220:223], v[32:35]
	v_mfma_f32_16x16x32_bf16 v[28:31], v[158:161], v[220:223], v[28:31]
	v_mfma_f32_16x16x32_bf16 v[16:19], v[150:153], v[228:231], v[16:19]
	v_mfma_f32_16x16x32_bf16 v[12:15], v[158:161], v[228:231], v[12:15]
	v_mfma_f32_16x16x32_bf16 v[56:59], v[162:165], v[178:181], v[56:59]
	v_mfma_f32_16x16x32_bf16 v[52:55], v[170:173], v[178:181], v[52:55]
	v_mfma_f32_16x16x32_bf16 v[40:43], v[162:165], v[186:189], v[40:43]
	v_mfma_f32_16x16x32_bf16 v[36:39], v[170:173], v[186:189], v[36:39]
	v_mfma_f32_16x16x32_bf16 v[24:27], v[162:165], v[204:207], v[24:27]
	v_mfma_f32_16x16x32_bf16 v[20:23], v[170:173], v[204:207], v[20:23]
	v_mfma_f32_16x16x32_bf16 v[8:11], v[162:165], v[224:227], v[8:11]
	v_mfma_f32_16x16x32_bf16 v[4:7], v[170:173], v[224:227], v[4:7]
	v_mfma_f32_16x16x32_bf16 v[56:59], v[166:169], v[182:185], v[56:59]
	v_mfma_f32_16x16x32_bf16 v[52:55], v[174:177], v[182:185], v[52:55]
	v_mfma_f32_16x16x32_bf16 v[40:43], v[166:169], v[190:193], v[40:43]
	v_mfma_f32_16x16x32_bf16 v[36:39], v[174:177], v[190:193], v[36:39]
	v_mfma_f32_16x16x32_bf16 v[24:27], v[166:169], v[220:223], v[24:27]
	v_mfma_f32_16x16x32_bf16 v[20:23], v[174:177], v[220:223], v[20:23]
	v_mfma_f32_16x16x32_bf16 v[8:11], v[166:169], v[228:231], v[8:11]
	v_mfma_f32_16x16x32_bf16 v[4:7], v[174:177], v[228:231], v[4:7]
	s_barrier
	s_add_i32 s69, 0, 0x18000
	s_add_i32 s70, 0, 0x1c000
	v_add_u32_e32 v158, s69, v147
	v_add_u32_e32 v174, s70, v147
	ds_read_b128 v[142:145], v158
	ds_read_b128 v[150:153], v158 offset:1024
	ds_read_b128 v[154:157], v158 offset:2048
	ds_read_b128 v[158:161], v158 offset:3072
	ds_read_b128 v[162:165], v174
	ds_read_b128 v[166:169], v174 offset:1024
	ds_read_b128 v[170:173], v174 offset:2048
	ds_read_b128 v[174:177], v174 offset:3072
	s_add_u32 s46, s46, 0x40000
	s_addc_u32 s47, s47, 0
	s_mov_b32 m0, s60
	v_lshl_add_u64 v[236:237], s[46:47], 0, v[132:133]
	ds_read_b128 v[178:181], v149 offset:32768
	ds_read_b128 v[182:185], v149 offset:33792
	ds_read_b128 v[186:189], v149 offset:34816
	ds_read_b128 v[190:193], v149 offset:35840
	ds_read_b128 v[204:207], v149 offset:36864
	ds_read_b128 v[220:223], v149 offset:37888
	ds_read_b128 v[224:227], v149 offset:38912
	ds_read_b128 v[228:231], v149 offset:39936
	global_load_lds_dwordx4 v[236:237], off
	v_lshl_add_u64 v[236:237], s[46:47], 0, v[134:135]
	s_mov_b32 m0, s61
	s_nop 0
	global_load_lds_dwordx4 v[236:237], off
	s_waitcnt vmcnt(8)
	s_waitcnt lgkmcnt(0)
	s_barrier
; #define PG8_STAGE(bufoff, gbase, voff) do { _Pragma("unroll") for (int _i = 0; _i < 2; ++_i) \
;         __builtin_amdgcn_global_load_lds((const unsigned*)((const char*)(gbase) + (voff)[_i]), (PG8_LAS unsigned*)(lds + (bufoff) + ldsw + _i * 8192), 16, 0, 0); } while (0)
; #define PG8_LDA(dst, b, h) do { _Pragma("unroll") for (int m = 0; m < 4; ++m) _Pragma("unroll") for (int k = 0; k < 2; ++k) dst[m][k] = *(const PG8_LAS bf16x8*)(lds + PG8_SA(b, h) + aoff + m * 2048 + k * 1024); } while (0)
; #define PG8_MMA(ai, bj, At, Bt) do { __builtin_amdgcn_s_setprio(1); _Pragma("unroll") for (int m = 0; m < 4; ++m) _Pragma("unroll") for (int n = 0; n < 2; ++n) _Pragma("unroll") for (int k = 0; k < 2; ++k) \
;         acc[ai][bj][m][n] = __builtin_amdgcn_mfma_f32_16x16x32_bf16(Bt[n][k], At[m][k], acc[ai][bj][m][n], 0, 0, 0); __builtin_amdgcn_s_setprio(0); } while (0)
; #define PG8_WAIT_V(n) asm volatile("s_waitcnt vmcnt(" #n ")" ::: "memory")
; #define PG8_WAIT_L(n) asm volatile("s_waitcnt lgkmcnt(" #n ")" ::: "memory")
; #define PG8_BAR __builtin_amdgcn_s_barrier()
; #define PG8_SCHED __builtin_amdgcn_sched_barrier(0)
; template <class Epi, class Sched, bool ALIGN_EPI = false, bool SP2 = false>
; __device__ __forceinline__ void gemm_phase(PG8_LAS unsigned char* lds, const Gemm g, const Sched& S, const Epi& E) {
;     ...
;             PG8_WAIT_V(8); PG8_WAIT_L(0); PG8_BAR; PG8_MMA(0, 0, At, B0); PG8_MMA(0, 1, At, B1); PG8_BAR; PG8_SCHED;
;             PG8_LDA(At, 1, 1); PG8_STAGE(PG8_SB(1, 0), b3, voffB); PG8_STAGE(PG8_SB(1, 1), b3 + hstep, voffB); PG8_STAGE(PG8_SA(1, 0), a3, voffA);
;             PG8_WAIT_V(8); PG8_WAIT_L(0); PG8_BAR; PG8_MMA(1, 0, At, B0); PG8_MMA(1, 1, At, B1); PG8_BAR; PG8_SCHED;
;     ...
;         if constexpr (ALIGN_EPI) { if (wr == 0) PG8_BAR; }
	s_waitcnt lgkmcnt(0)
	v_mfma_f32_16x16x32_bf16 v[128:131], v[142:145], v[178:181], v[128:131]
	v_mfma_f32_16x16x32_bf16 v[124:127], v[154:157], v[178:181], v[124:127]
	v_mfma_f32_16x16x32_bf16 v[112:115], v[142:145], v[186:189], v[112:115]
	v_mfma_f32_16x16x32_bf16 v[108:111], v[154:157], v[186:189], v[108:111]
	v_mfma_f32_16x16x32_bf16 v[96:99], v[142:145], v[204:207], v[96:99]
	v_mfma_f32_16x16x32_bf16 v[92:95], v[154:157], v[204:207], v[92:95]
	v_mfma_f32_16x16x32_bf16 v[80:83], v[142:145], v[224:227], v[80:83]
	v_mfma_f32_16x16x32_bf16 v[76:79], v[154:157], v[224:227], v[76:79]
	v_mfma_f32_16x16x32_bf16 v[128:131], v[150:153], v[182:185], v[128:131]
	v_mfma_f32_16x16x32_bf16 v[124:127], v[158:161], v[182:185], v[124:127]
	v_mfma_f32_16x16x32_bf16 v[112:115], v[150:153], v[190:193], v[112:115]
	v_mfma_f32_16x16x32_bf16 v[108:111], v[158:161], v[190:193], v[108:111]
	v_mfma_f32_16x16x32_bf16 v[96:99], v[150:153], v[220:223], v[96:99]
	v_mfma_f32_16x16x32_bf16 v[92:95], v[158:161], v[220:223], v[92:95]
	v_mfma_f32_16x16x32_bf16 v[80:83], v[150:153], v[228:231], v[80:83]
	v_mfma_f32_16x16x32_bf16 v[76:79], v[158:161], v[228:231], v[76:79]
	v_mfma_f32_16x16x32_bf16 v[120:123], v[162:165], v[178:181], v[120:123]
	v_mfma_f32_16x16x32_bf16 v[116:119], v[170:173], v[178:181], v[116:119]
	v_mfma_f32_16x16x32_bf16 v[104:107], v[162:165], v[186:189], v[104:107]
	v_mfma_f32_16x16x32_bf16 v[100:103], v[170:173], v[186:189], v[100:103]
	v_mfma_f32_16x16x32_bf16 v[88:91], v[162:165], v[204:207], v[88:91]
	v_mfma_f32_16x16x32_bf16 v[84:87], v[170:173], v[204:207], v[84:87]
	v_mfma_f32_16x16x32_bf16 v[72:75], v[162:165], v[224:227], v[72:75]
	v_mfma_f32_16x16x32_bf16 v[68:71], v[170:173], v[224:227], v[68:71]
	v_mfma_f32_16x16x32_bf16 v[120:123], v[166:169], v[182:185], v[120:123]
	v_mfma_f32_16x16x32_bf16 v[116:119], v[174:177], v[182:185], v[116:119]
	v_mfma_f32_16x16x32_bf16 v[104:107], v[166:169], v[190:193], v[104:107]
	v_mfma_f32_16x16x32_bf16 v[100:103], v[174:177], v[190:193], v[100:103]
	v_mfma_f32_16x16x32_bf16 v[88:91], v[166:169], v[220:223], v[88:91]
	v_mfma_f32_16x16x32_bf16 v[84:87], v[174:177], v[220:223], v[84:87]
	v_mfma_f32_16x16x32_bf16 v[72:75], v[166:169], v[228:231], v[72:75]
	v_mfma_f32_16x16x32_bf16 v[68:71], v[174:177], v[228:231], v[68:71]
	s_barrier
	s_add_i32 s46, s69, s56
	v_lshl_add_u64 v[194:195], v[194:195], 0, s[92:93]
	s_mov_b32 m0, s46
	ds_read_b128 v[178:181], v149 offset:49152
	ds_read_b128 v[182:185], v149 offset:50176
	ds_read_b128 v[186:189], v149 offset:51200
	ds_read_b128 v[190:193], v149 offset:52224
	ds_read_b128 v[204:207], v149 offset:53248
	ds_read_b128 v[220:223], v149 offset:54272
	ds_read_b128 v[224:227], v149 offset:55296
	ds_read_b128 v[228:231], v149 offset:56320
	global_load_lds_dwordx4 v[194:195], off
	s_add_i32 m0, s46, 0x2000
	s_add_u32 s44, s44, 0x40080
	v_lshl_add_u64 v[194:195], v[196:197], 0, s[92:93]
	s_addc_u32 s45, s45, 0
	s_add_i32 s46, s70, s56
	global_load_lds_dwordx4 v[194:195], off
	v_lshl_add_u64 v[194:195], s[44:45], 0, v[2:3]
	s_mov_b32 m0, s46
	s_nop 0
	global_load_lds_dwordx4 v[194:195], off
	v_lshl_add_u64 v[194:195], s[44:45], 0, v[136:137]
	s_add_i32 m0, s46, 0x2000
	s_nop 0
	global_load_lds_dwordx4 v[194:195], off
	v_lshl_add_u64 v[194:195], v[232:233], 0, s[92:93]
	s_mov_b32 m0, s62
	s_nop 0
	global_load_lds_dwordx4 v[194:195], off
	v_lshl_add_u64 v[194:195], v[234:235], 0, s[92:93]
	s_mov_b32 m0, s63
	s_nop 0
	global_load_lds_dwordx4 v[194:195], off
	s_waitcnt vmcnt(8)
	s_waitcnt lgkmcnt(0)
	s_barrier
	s_waitcnt lgkmcnt(0)
	v_mfma_f32_16x16x32_bf16 v[64:67], v[142:145], v[178:181], v[64:67]
	v_mfma_f32_16x16x32_bf16 v[60:63], v[154:157], v[178:181], v[60:63]
	v_mfma_f32_16x16x32_bf16 v[48:51], v[142:145], v[186:189], v[48:51]
	v_mfma_f32_16x16x32_bf16 v[44:47], v[154:157], v[186:189], v[44:47]
	v_mfma_f32_16x16x32_bf16 v[32:35], v[142:145], v[204:207], v[32:35]
	v_mfma_f32_16x16x32_bf16 v[28:31], v[154:157], v[204:207], v[28:31]
	v_mfma_f32_16x16x32_bf16 v[16:19], v[142:145], v[224:227], v[16:19]
	v_mfma_f32_16x16x32_bf16 v[12:15], v[154:157], v[224:227], v[12:15]
	v_mfma_f32_16x16x32_bf16 v[64:67], v[150:153], v[182:185], v[64:67]
	v_mfma_f32_16x16x32_bf16 v[60:63], v[158:161], v[182:185], v[60:63]
	v_mfma_f32_16x16x32_bf16 v[48:51], v[150:153], v[190:193], v[48:51]
	v_mfma_f32_16x16x32_bf16 v[44:47], v[158:161], v[190:193], v[44:47]
	v_mfma_f32_16x16x32_bf16 v[32:35], v[150:153], v[220:223], v[32:35]
	v_mfma_f32_16x16x32_bf16 v[28:31], v[158:161], v[220:223], v[28:31]
	v_mfma_f32_16x16x32_bf16 v[16:19], v[150:153], v[228:231], v[16:19]
	v_mfma_f32_16x16x32_bf16 v[12:15], v[158:161], v[228:231], v[12:15]
	v_mfma_f32_16x16x32_bf16 v[56:59], v[162:165], v[178:181], v[56:59]
	v_mfma_f32_16x16x32_bf16 v[52:55], v[170:173], v[178:181], v[52:55]
	v_mfma_f32_16x16x32_bf16 v[40:43], v[162:165], v[186:189], v[40:43]
	v_mfma_f32_16x16x32_bf16 v[36:39], v[170:173], v[186:189], v[36:39]
	v_mfma_f32_16x16x32_bf16 v[24:27], v[162:165], v[204:207], v[24:27]
	v_mfma_f32_16x16x32_bf16 v[20:23], v[170:173], v[204:207], v[20:23]
	v_mfma_f32_16x16x32_bf16 v[8:11], v[162:165], v[224:227], v[8:11]
	v_mfma_f32_16x16x32_bf16 v[4:7], v[170:173], v[224:227], v[4:7]
	v_mfma_f32_16x16x32_bf16 v[56:59], v[166:169], v[182:185], v[56:59]
	v_mfma_f32_16x16x32_bf16 v[52:55], v[174:177], v[182:185], v[52:55]
	v_mfma_f32_16x16x32_bf16 v[40:43], v[166:169], v[190:193], v[40:43]
	v_mfma_f32_16x16x32_bf16 v[36:39], v[174:177], v[190:193], v[36:39]
	v_mfma_f32_16x16x32_bf16 v[24:27], v[166:169], v[220:223], v[24:27]
	v_mfma_f32_16x16x32_bf16 v[20:23], v[174:177], v[220:223], v[20:23]
	v_mfma_f32_16x16x32_bf16 v[8:11], v[166:169], v[228:231], v[8:11]
	v_mfma_f32_16x16x32_bf16 v[4:7], v[174:177], v[228:231], v[4:7]
	s_barrier
	s_add_i32 s68, s68, 2
	s_add_u32 s42, s42, 0x100
	s_addc_u32 s43, s43, 0
	s_add_u32 s66, s66, 0x100
	s_addc_u32 s67, s67, 0
	s_cmp_gt_u32 s68, 13
	s_cbranch_scc0 .LBB0_685
	s_and_b64 vcc, exec, s[28:29]
	s_cbranch_vccz .LBB0_688
	s_barrier
; __device__ __forceinline__ unsigned cvt_pk_bf16(float lo, float hi) { unsigned r; asm volatile("v_cvt_pk_bf16_f32 %0, %1, %2" : "=v"(r) : "v"(lo), "v"(hi)); return r; }
;     __device__ __forceinline__ void operator()(const f32x4 (&acc)[2][2][4][2], const Unit& u, int wr, int wc, int fr, int fq) const {
;         const int row0 = u.pm * BM + wr * 64 + fr, col0 = u.pn * BM + wc * 32 + 8 * fq;
; #pragma unroll
;         for (int ai = 0; ai < 2; ++ai)
; #pragma unroll
;             for (int m = 0; m < 4; ++m) { const int row = row0 + ai * HALF + m * 16; const f32x4 q0 = *(const f32x4*)(ssq + (size_t)row * 16), q1 = *(const f32x4*)(ssq + (size_t)row * 16 + 4), q2 = *(const f32x4*)(ssq + (size_t)row * 16 + 8), q3 = *(const f32x4*)(ssq + (size_t)row * 16 + 12);
;                 const float rs = rsqrtf(((((q0[0] + q0[1]) + (q0[2] + q0[3])) + ((q1[0] + q1[1]) + (q1[2] + q1[3]))) + (((q2[0] + q2[1]) + (q2[2] + q2[3])) + ((q3[0] + q3[1]) + (q3[2] + q3[3])))) * (1.0f / 1024.0f) + 1e-6f);
;                 bf16_t* rowp = O + (size_t)row * ldc + col0;
; #pragma unroll
;                 for (int bj = 0; bj < 2; ++bj) { const f32x4 v0 = acc[ai][bj][m][0] * rs, v1 = acc[ai][bj][m][1] * rs;
;                     u32x4 w; w.x = cvt_pk_bf16(v0[0], v0[1]); w.y = cvt_pk_bf16(v0[2], v0[3]); w.z = cvt_pk_bf16(v1[0], v1[1]); w.w = cvt_pk_bf16(v1[2], v1[3]);
;                     *(u32x4*)(rowp + bj * HALF) = w; } }
.LBB0_688:
	s_setprio 0
	v_lshl_add_u32 v190, s40, 8, v146
	v_and_b32_e32 v191, 24, v148
	v_lshlrev_b32_e32 v191, 1, v191
	v_lshl_add_u32 v191, v190, 6, v191
	v_add_u32_e32 v230, 0x2000, v191
	global_load_dwordx4 v[150:153], v191, s[22:23]
	global_load_dwordx4 v[154:157], v191, s[22:23] offset:1024
	global_load_dwordx4 v[158:161], v191, s[22:23] offset:2048
	global_load_dwordx4 v[162:165], v191, s[22:23] offset:3072
	global_load_dwordx4 v[166:169], v230, s[22:23]
	global_load_dwordx4 v[170:173], v230, s[22:23] offset:1024
	global_load_dwordx4 v[174:177], v230, s[22:23] offset:2048
	global_load_dwordx4 v[178:181], v230, s[22:23] offset:3072
	v_xor_b32_e32 v228, 16, v214
	v_lshlrev_b32_e32 v228, 2, v228
	v_xor_b32_e32 v229, 32, v214
	v_lshlrev_b32_e32 v229, 2, v229
	s_lshl_b32 s31, s50, 1
	v_lshl_or_b32 v231, s41, 8, v148
	v_lshlrev_b32_e32 v231, 1, v231
	v_mad_u32_u24 v182, v190, s31, v231
	s_lshl_b32 s99, s50, 5
	v_add_u32_e32 v183, s99, v182
	v_add_u32_e32 v184, s99, v183
	v_add_u32_e32 v185, s99, v184
	s_lshl_b32 s99, s50, 8
	v_add_u32_e32 v186, s99, v182
	v_add_u32_e32 v187, s99, v183
	v_add_u32_e32 v188, s99, v184
	v_add_u32_e32 v189, s99, v185
	s_waitcnt vmcnt(7)
	v_add_f32_e32 v152, v152, v153
	v_add_f32_e32 v192, v150, v151
	v_add_f32_e32 v192, v192, v152
	s_waitcnt vmcnt(6)
	v_add_f32_e32 v156, v156, v157
	v_add_f32_e32 v193, v154, v155
	v_add_f32_e32 v193, v193, v156
	s_waitcnt vmcnt(5)
	v_add_f32_e32 v160, v160, v161
	v_add_f32_e32 v194, v158, v159
	v_add_f32_e32 v194, v194, v160
	s_waitcnt vmcnt(4)
	v_add_f32_e32 v164, v164, v165
	v_add_f32_e32 v195, v162, v163
	v_add_f32_e32 v195, v195, v164
	s_waitcnt vmcnt(3)
	v_add_f32_e32 v168, v168, v169
	v_add_f32_e32 v196, v166, v167
	v_add_f32_e32 v196, v196, v168
	s_waitcnt vmcnt(2)
	v_add_f32_e32 v172, v172, v173
	v_add_f32_e32 v197, v170, v171
	v_add_f32_e32 v197, v197, v172
	s_waitcnt vmcnt(1)
	v_add_f32_e32 v176, v176, v177
	v_add_f32_e32 v204, v174, v175
	v_add_f32_e32 v204, v204, v176
	s_waitcnt vmcnt(0)
	v_add_f32_e32 v180, v180, v181
	v_add_f32_e32 v205, v178, v179
	v_add_f32_e32 v205, v205, v180
	ds_bpermute_b32 v220, v228, v192
	ds_bpermute_b32 v221, v228, v193
	ds_bpermute_b32 v222, v228, v194
	ds_bpermute_b32 v223, v228, v195
	ds_bpermute_b32 v224, v228, v196
	ds_bpermute_b32 v225, v228, v197
	ds_bpermute_b32 v226, v228, v204
	ds_bpermute_b32 v227, v228, v205
	s_waitcnt lgkmcnt(7)
	v_add_f32_e32 v192, v192, v220
	s_waitcnt lgkmcnt(6)
	v_add_f32_e32 v193, v193, v221
	s_waitcnt lgkmcnt(5)
	v_add_f32_e32 v194, v194, v222
	s_waitcnt lgkmcnt(4)
	v_add_f32_e32 v195, v195, v223
	s_waitcnt lgkmcnt(3)
	v_add_f32_e32 v196, v196, v224
	s_waitcnt lgkmcnt(2)
	v_add_f32_e32 v197, v197, v225
	s_waitcnt lgkmcnt(1)
	v_add_f32_e32 v204, v204, v226
	s_waitcnt lgkmcnt(0)
	v_add_f32_e32 v205, v205, v227
	ds_bpermute_b32 v220, v229, v192
	ds_bpermute_b32 v221, v229, v193
	ds_bpermute_b32 v222, v229, v194
	ds_bpermute_b32 v223, v229, v195
	ds_bpermute_b32 v224, v229, v196
	ds_bpermute_b32 v225, v229, v197
	ds_bpermute_b32 v226, v229, v204
	ds_bpermute_b32 v227, v229, v205
	s_waitcnt lgkmcnt(7)
	v_add_f32_e32 v192, v192, v220
	s_waitcnt lgkmcnt(6)
	v_add_f32_e32 v193, v193, v221
	s_waitcnt lgkmcnt(5)
	v_add_f32_e32 v194, v194, v222
	s_waitcnt lgkmcnt(4)
	v_add_f32_e32 v195, v195, v223
	s_waitcnt lgkmcnt(3)
	v_add_f32_e32 v196, v196, v224
	s_waitcnt lgkmcnt(2)
	v_add_f32_e32 v197, v197, v225
	s_waitcnt lgkmcnt(1)
	v_add_f32_e32 v204, v204, v226
	s_waitcnt lgkmcnt(0)
	v_add_f32_e32 v205, v205, v227
	v_fmamk_f32 v192, v192, 0x3a800000, v208
	v_fmamk_f32 v193, v193, 0x3a800000, v208
	v_fmamk_f32 v194, v194, 0x3a800000, v208
	v_fmamk_f32 v195, v195, 0x3a800000, v208
	v_fmamk_f32 v196, v196, 0x3a800000, v208
	v_fmamk_f32 v197, v197, 0x3a800000, v208
	v_fmamk_f32 v204, v204, 0x3a800000, v208
	v_fmamk_f32 v205, v205, 0x3a800000, v208
	v_rsq_f32_e32 v150, v192
	v_rsq_f32_e32 v154, v193
	v_rsq_f32_e32 v158, v194
	v_rsq_f32_e32 v162, v195
	v_rsq_f32_e32 v166, v196
	v_rsq_f32_e32 v170, v197
	v_rsq_f32_e32 v174, v204
	v_rsq_f32_e32 v178, v205
	v_pk_mul_f32 v[128:129], v[128:129], v[150:151] op_sel_hi:[1,0]
	v_pk_mul_f32 v[130:131], v[130:131], v[150:151] op_sel_hi:[1,0]
	v_pk_mul_f32 v[124:125], v[124:125], v[150:151] op_sel_hi:[1,0]
	v_pk_mul_f32 v[126:127], v[126:127], v[150:151] op_sel_hi:[1,0]
	v_cvt_pk_bf16_f32 v128, v128, v129
	v_cvt_pk_bf16_f32 v129, v130, v131
	v_cvt_pk_bf16_f32 v130, v124, v125
	v_cvt_pk_bf16_f32 v131, v126, v127
	global_store_dwordx4 v182, v[128:131], s[18:19]
	v_pk_mul_f32 v[120:121], v[120:121], v[150:151] op_sel_hi:[1,0]
	v_pk_mul_f32 v[122:123], v[122:123], v[150:151] op_sel_hi:[1,0]
	v_pk_mul_f32 v[116:117], v[116:117], v[150:151] op_sel_hi:[1,0]
	v_pk_mul_f32 v[118:119], v[118:119], v[150:151] op_sel_hi:[1,0]
	v_cvt_pk_bf16_f32 v120, v120, v121
	v_cvt_pk_bf16_f32 v121, v122, v123
	v_cvt_pk_bf16_f32 v122, v116, v117
	v_cvt_pk_bf16_f32 v123, v118, v119
	global_store_dwordx4 v182, v[120:123], s[18:19] offset:256
	v_pk_mul_f32 v[112:113], v[112:113], v[154:155] op_sel_hi:[1,0]
	v_pk_mul_f32 v[114:115], v[114:115], v[154:155] op_sel_hi:[1,0]
	v_pk_mul_f32 v[108:109], v[108:109], v[154:155] op_sel_hi:[1,0]
	v_pk_mul_f32 v[110:111], v[110:111], v[154:155] op_sel_hi:[1,0]
	v_cvt_pk_bf16_f32 v112, v112, v113
	v_cvt_pk_bf16_f32 v113, v114, v115
	v_cvt_pk_bf16_f32 v114, v108, v109
	v_cvt_pk_bf16_f32 v115, v110, v111
	global_store_dwordx4 v183, v[112:115], s[18:19]
	v_pk_mul_f32 v[104:105], v[104:105], v[154:155] op_sel_hi:[1,0]
	v_pk_mul_f32 v[106:107], v[106:107], v[154:155] op_sel_hi:[1,0]
	v_pk_mul_f32 v[100:101], v[100:101], v[154:155] op_sel_hi:[1,0]
; __device__ __forceinline__ unsigned cvt_pk_bf16(float lo, float hi) { unsigned r; asm volatile("v_cvt_pk_bf16_f32 %0, %1, %2" : "=v"(r) : "v"(lo), "v"(hi)); return r; }
; #define PG8_BAR __builtin_amdgcn_s_barrier()
;     __device__ __forceinline__ void operator()(const f32x4 (&acc)[2][2][4][2], const Unit& u, int wr, int wc, int fr, int fq) const {
;     ...
;                 for (int bj = 0; bj < 2; ++bj) { const f32x4 v0 = acc[ai][bj][m][0] * rs, v1 = acc[ai][bj][m][1] * rs;
;                     u32x4 w; w.x = cvt_pk_bf16(v0[0], v0[1]); w.y = cvt_pk_bf16(v0[2], v0[3]); w.z = cvt_pk_bf16(v1[0], v1[1]); w.w = cvt_pk_bf16(v1[2], v1[3]);
;                     *(u32x4*)(rowp + bj * HALF) = w; } }
; template <class Epi, class Sched, bool ALIGN_EPI = false, bool SP2 = false>
; __device__ __forceinline__ void gemm_phase(PG8_LAS unsigned char* lds, const Gemm g, const Sched& S, const Epi& E) {
;     ...
;         if (!has_next) break;
; #pragma unroll
;         for (int a = 0; a < 2; ++a)
; #pragma unroll
;             for (int b = 0; b < 2; ++b)
; #pragma unroll
;                 for (int m = 0; m < 4; ++m)
; #pragma unroll
;                     for (int n = 0; n < 2; ++n) acc[a][b][m][n] = (f32x4){0.f, 0.f, 0.f, 0.f};
;         cur = nxt; cA = nA; cB = nB; ++ui;
;         if constexpr (ALIGN_EPI) { if (wr == 1) PG8_BAR; }
	v_pk_mul_f32 v[102:103], v[102:103], v[154:155] op_sel_hi:[1,0]
	v_cvt_pk_bf16_f32 v104, v104, v105
	v_cvt_pk_bf16_f32 v105, v106, v107
	v_cvt_pk_bf16_f32 v106, v100, v101
	v_cvt_pk_bf16_f32 v107, v102, v103
	global_store_dwordx4 v183, v[104:107], s[18:19] offset:256
	v_pk_mul_f32 v[96:97], v[96:97], v[158:159] op_sel_hi:[1,0]
	v_pk_mul_f32 v[98:99], v[98:99], v[158:159] op_sel_hi:[1,0]
	v_pk_mul_f32 v[92:93], v[92:93], v[158:159] op_sel_hi:[1,0]
	v_pk_mul_f32 v[94:95], v[94:95], v[158:159] op_sel_hi:[1,0]
	v_cvt_pk_bf16_f32 v96, v96, v97
	v_cvt_pk_bf16_f32 v97, v98, v99
	v_cvt_pk_bf16_f32 v98, v92, v93
	v_cvt_pk_bf16_f32 v99, v94, v95
	global_store_dwordx4 v184, v[96:99], s[18:19]
	v_pk_mul_f32 v[88:89], v[88:89], v[158:159] op_sel_hi:[1,0]
	v_pk_mul_f32 v[90:91], v[90:91], v[158:159] op_sel_hi:[1,0]
	v_pk_mul_f32 v[84:85], v[84:85], v[158:159] op_sel_hi:[1,0]
	v_pk_mul_f32 v[86:87], v[86:87], v[158:159] op_sel_hi:[1,0]
	v_cvt_pk_bf16_f32 v88, v88, v89
	v_cvt_pk_bf16_f32 v89, v90, v91
	v_cvt_pk_bf16_f32 v90, v84, v85
	v_cvt_pk_bf16_f32 v91, v86, v87
	global_store_dwordx4 v184, v[88:91], s[18:19] offset:256
	v_pk_mul_f32 v[80:81], v[80:81], v[162:163] op_sel_hi:[1,0]
	v_pk_mul_f32 v[82:83], v[82:83], v[162:163] op_sel_hi:[1,0]
	v_pk_mul_f32 v[76:77], v[76:77], v[162:163] op_sel_hi:[1,0]
	v_pk_mul_f32 v[78:79], v[78:79], v[162:163] op_sel_hi:[1,0]
	v_cvt_pk_bf16_f32 v80, v80, v81
	v_cvt_pk_bf16_f32 v81, v82, v83
	v_cvt_pk_bf16_f32 v82, v76, v77
	v_cvt_pk_bf16_f32 v83, v78, v79
	global_store_dwordx4 v185, v[80:83], s[18:19]
	v_pk_mul_f32 v[72:73], v[72:73], v[162:163] op_sel_hi:[1,0]
	v_pk_mul_f32 v[74:75], v[74:75], v[162:163] op_sel_hi:[1,0]
	v_pk_mul_f32 v[68:69], v[68:69], v[162:163] op_sel_hi:[1,0]
	v_pk_mul_f32 v[70:71], v[70:71], v[162:163] op_sel_hi:[1,0]
	v_cvt_pk_bf16_f32 v72, v72, v73
	v_cvt_pk_bf16_f32 v73, v74, v75
	v_cvt_pk_bf16_f32 v74, v68, v69
	v_cvt_pk_bf16_f32 v75, v70, v71
	global_store_dwordx4 v185, v[72:75], s[18:19] offset:256
	v_pk_mul_f32 v[64:65], v[64:65], v[166:167] op_sel_hi:[1,0]
	v_pk_mul_f32 v[66:67], v[66:67], v[166:167] op_sel_hi:[1,0]
	v_pk_mul_f32 v[60:61], v[60:61], v[166:167] op_sel_hi:[1,0]
	v_pk_mul_f32 v[62:63], v[62:63], v[166:167] op_sel_hi:[1,0]
	v_cvt_pk_bf16_f32 v64, v64, v65
	v_cvt_pk_bf16_f32 v65, v66, v67
	v_cvt_pk_bf16_f32 v66, v60, v61
	v_cvt_pk_bf16_f32 v67, v62, v63
	global_store_dwordx4 v186, v[64:67], s[18:19]
	v_pk_mul_f32 v[56:57], v[56:57], v[166:167] op_sel_hi:[1,0]
	v_pk_mul_f32 v[58:59], v[58:59], v[166:167] op_sel_hi:[1,0]
	v_pk_mul_f32 v[52:53], v[52:53], v[166:167] op_sel_hi:[1,0]
	v_pk_mul_f32 v[54:55], v[54:55], v[166:167] op_sel_hi:[1,0]
	v_cvt_pk_bf16_f32 v56, v56, v57
	v_cvt_pk_bf16_f32 v57, v58, v59
	v_cvt_pk_bf16_f32 v58, v52, v53
	v_cvt_pk_bf16_f32 v59, v54, v55
	global_store_dwordx4 v186, v[56:59], s[18:19] offset:256
	v_pk_mul_f32 v[48:49], v[48:49], v[170:171] op_sel_hi:[1,0]
	v_pk_mul_f32 v[50:51], v[50:51], v[170:171] op_sel_hi:[1,0]
	v_pk_mul_f32 v[44:45], v[44:45], v[170:171] op_sel_hi:[1,0]
	v_pk_mul_f32 v[46:47], v[46:47], v[170:171] op_sel_hi:[1,0]
	v_cvt_pk_bf16_f32 v48, v48, v49
	v_cvt_pk_bf16_f32 v49, v50, v51
	v_cvt_pk_bf16_f32 v50, v44, v45
	v_cvt_pk_bf16_f32 v51, v46, v47
	global_store_dwordx4 v187, v[48:51], s[18:19]
	v_pk_mul_f32 v[40:41], v[40:41], v[170:171] op_sel_hi:[1,0]
	v_pk_mul_f32 v[42:43], v[42:43], v[170:171] op_sel_hi:[1,0]
	v_pk_mul_f32 v[36:37], v[36:37], v[170:171] op_sel_hi:[1,0]
	v_pk_mul_f32 v[38:39], v[38:39], v[170:171] op_sel_hi:[1,0]
	v_cvt_pk_bf16_f32 v40, v40, v41
	v_cvt_pk_bf16_f32 v41, v42, v43
	v_cvt_pk_bf16_f32 v42, v36, v37
	v_cvt_pk_bf16_f32 v43, v38, v39
	global_store_dwordx4 v187, v[40:43], s[18:19] offset:256
	v_pk_mul_f32 v[32:33], v[32:33], v[174:175] op_sel_hi:[1,0]
	v_pk_mul_f32 v[34:35], v[34:35], v[174:175] op_sel_hi:[1,0]
	v_pk_mul_f32 v[28:29], v[28:29], v[174:175] op_sel_hi:[1,0]
	v_pk_mul_f32 v[30:31], v[30:31], v[174:175] op_sel_hi:[1,0]
	v_cvt_pk_bf16_f32 v32, v32, v33
	v_cvt_pk_bf16_f32 v33, v34, v35
	v_cvt_pk_bf16_f32 v34, v28, v29
	v_cvt_pk_bf16_f32 v35, v30, v31
	global_store_dwordx4 v188, v[32:35], s[18:19]
	v_pk_mul_f32 v[24:25], v[24:25], v[174:175] op_sel_hi:[1,0]
	v_pk_mul_f32 v[26:27], v[26:27], v[174:175] op_sel_hi:[1,0]
	v_pk_mul_f32 v[20:21], v[20:21], v[174:175] op_sel_hi:[1,0]
	v_pk_mul_f32 v[22:23], v[22:23], v[174:175] op_sel_hi:[1,0]
	v_cvt_pk_bf16_f32 v24, v24, v25
	v_cvt_pk_bf16_f32 v25, v26, v27
	v_cvt_pk_bf16_f32 v26, v20, v21
	v_cvt_pk_bf16_f32 v27, v22, v23
	global_store_dwordx4 v188, v[24:27], s[18:19] offset:256
	v_pk_mul_f32 v[16:17], v[16:17], v[178:179] op_sel_hi:[1,0]
	v_pk_mul_f32 v[18:19], v[18:19], v[178:179] op_sel_hi:[1,0]
	v_pk_mul_f32 v[12:13], v[12:13], v[178:179] op_sel_hi:[1,0]
	v_pk_mul_f32 v[14:15], v[14:15], v[178:179] op_sel_hi:[1,0]
	v_cvt_pk_bf16_f32 v16, v16, v17
	v_cvt_pk_bf16_f32 v17, v18, v19
	v_cvt_pk_bf16_f32 v18, v12, v13
	v_cvt_pk_bf16_f32 v19, v14, v15
	global_store_dwordx4 v189, v[16:19], s[18:19]
	v_pk_mul_f32 v[8:9], v[8:9], v[178:179] op_sel_hi:[1,0]
	v_pk_mul_f32 v[10:11], v[10:11], v[178:179] op_sel_hi:[1,0]
	v_pk_mul_f32 v[4:5], v[4:5], v[178:179] op_sel_hi:[1,0]
	v_pk_mul_f32 v[6:7], v[6:7], v[178:179] op_sel_hi:[1,0]
	v_cvt_pk_bf16_f32 v8, v8, v9
	v_cvt_pk_bf16_f32 v9, v10, v11
	v_cvt_pk_bf16_f32 v10, v4, v5
	v_cvt_pk_bf16_f32 v11, v6, v7
	global_store_dwordx4 v189, v[8:11], s[18:19] offset:256
	s_mov_b32 s31, 0x800000
	s_mov_b32 s99, 0x800000
	s_mov_b32 s70, 0xbfb8aa3b
	s_movk_i32 s71, 0x1c00
	s_movk_i32 s73, 0x5a
	s_mov_b64 s[40:41], -1
	s_andn2_b64 vcc, exec, s[2:3]
	s_cbranch_vccnz .LBB0_681
	s_andn2_b64 vcc, exec, s[26:27]
	s_cbranch_vccnz .LBB0_680
	s_barrier
	s_branch .LBB0_680

; #define LAS __attribute__((address_space(3)))
; template <bool OUT>
; __device__ __forceinline__ void mlstm_item(const bf16* u, bf16* y, float* scratch, const float* convw, const float* ib, const float* fbias, const float* normw, LAS unsigned char* wl, int bh, int c, int lane) {
;     const int b = bh / 6, h = bh % 6, r = lane & 31, hi = lane >> 5;
;     const bf16* ub = u + (size_t)b * S * NU;
;     LAS float* cw = (LAS float*)(wl + ML_CW); LAS float* eb = (LAS float*)(wl + ML_EB); LAS float* nl = (LAS float*)(wl + ML_NL); LAS float* nwl = (LAS float*)(wl + ML_NW);
; __global__ void __launch_bounds__(512, 2) mega_fwd(Args a) {
;     ...
;                     if (isc) { const int ci = it - 522; __builtin_amdgcn_s_setprio(2); mlstm_item<true>(ub, yb, mscr, prm + 512, prm + 8, prm + 16, prm + 64, L + wave * ML_WSTRIDE, xcd + 8 * (ci >> 4), 15 - (ci & 15), lane); __builtin_amdgcn_s_setprio(0); }
.LBB0_780:
	s_lshr_b32 s0, s3, 1
	s_and_b32 s0, s0, 0xfff8
	s_or_b32 s0, s0, s69
	s_and_b32 s1, s0, 0xff
	s_mulk_i32 s1, 0xab
	s_lshr_b32 s50, s1, 10
	s_mul_i32 s1, s50, 6
	s_sub_i32 s0, s0, s1
	s_and_b32 s33, s0, 0xff
	s_lshl_b32 s52, s33, 6
	s_add_i32 s51, s52, 0x140
	s_mov_b64 s[0:1], 0
	v_mov_b32_e32 v1, v220
	v_mov_b32_e32 v4, v202

; #define LAS __attribute__((address_space(3)))
; __device__ __forceinline__ float bf2f(unsigned short v) { return __uint_as_float(((unsigned)v) << 16); }
; __device__ __forceinline__ s16x4 tr_read(LAS const unsigned char* p) { return __builtin_bit_cast(s16x4, __builtin_amdgcn_ds_read_tr16_b64_v4i16((LAS s16x4*)p)); }
; __device__ __forceinline__ s16x8 cat8(s16x4 a, s16x4 b) { return (s16x8){a[0], a[1], a[2], a[3], b[0], b[1], b[2], b[3]}; }
; #define MFMA32(a, b, c) __builtin_amdgcn_mfma_f32_32x32x16_bf16(a, b, c, 0, 0, 0)
; template <bool OUT>
; __device__ __forceinline__ void mlstm_item(const bf16* u, bf16* y, float* scratch, const float* convw, const float* ib, const float* fbias, const float* normw, LAS unsigned char* wl, int bh, int c, int lane) {
;     ...
; #pragma unroll
;           for (int kb = 0; kb < 2; ++kb)
; #pragma unroll
;               for (int vb = 0; vb < 2; ++vb) { X[kb][vb] *= eg;
; #pragma unroll
;                   for (int sp = 0; sp < 2; ++sp) { LAS const unsigned char* kp = wl + ML_WK + trN + 16 * sp * 144 + 64 * kb; LAS const unsigned char* vp = wl + ML_V + trN + 16 * sp * 144 + 64 * vb;
;                       X[kb][vb] = MFMA32(cat8(tr_read(kp), tr_read(kp + 4 * 144)), cat8(tr_read(vp), tr_read(vp + 4 * 144)), X[kb][vb]); } }
;           float dn = 0.f;
; #pragma unroll 8
;           for (int s2 = 0; s2 < 32; ++s2) dn += bf2f(*(LAS const unsigned short*)(wl + ML_WK + s2 * 144 + 2 * lane));
;           nk = eg * nk + dn; nl[lane] = nk; }
.LBB0_792:
	ds_read_u16 v126, v221
	ds_read_u16 v127, v221 offset:144
	ds_read_u16 v128, v221 offset:288
	ds_read_u16 v129, v221 offset:432
	ds_read_u16 v130, v221 offset:576
	ds_read_u16 v131, v221 offset:720
	ds_read_u16 v132, v221 offset:864
	ds_read_u16 v133, v221 offset:1008
	ds_read_u16 v134, v221 offset:1152
	ds_read_u16 v135, v221 offset:1296
	ds_read_u16 v136, v221 offset:1440
	ds_read_u16 v137, v221 offset:1584
	ds_read_u16 v138, v221 offset:1728
	ds_read_u16 v139, v221 offset:1872
	ds_read_u16 v166, v221 offset:2016
	ds_read_u16 v167, v221 offset:2160
	ds_read_u16 v168, v221 offset:2304
	ds_read_u16 v169, v221 offset:2448
	ds_read_u16 v170, v221 offset:2592
	ds_read_u16 v171, v221 offset:2736
	ds_read_u16 v172, v221 offset:2880
	ds_read_u16 v173, v221 offset:3024
	ds_read_u16 v174, v221 offset:3168
	ds_read_u16 v175, v221 offset:3312
	ds_read_u16 v176, v221 offset:3456
	ds_read_u16 v177, v221 offset:3600
	ds_read_u16 v178, v221 offset:3744
	ds_read_u16 v179, v221 offset:3888
	ds_read_u16 v180, v221 offset:4032
	ds_read_u16 v181, v221 offset:4176
	ds_read_u16 v182, v221 offset:4320
	ds_read_u16 v233, v221 offset:4464
	s_waitcnt lgkmcnt(15)
	v_lshlrev_b32_e32 v126, 16, v126
	v_add_f32_e32 v2, v2, v126
	v_lshlrev_b32_e32 v127, 16, v127
	v_add_f32_e32 v2, v2, v127
	v_lshlrev_b32_e32 v128, 16, v128
	v_add_f32_e32 v2, v2, v128
	v_lshlrev_b32_e32 v129, 16, v129
	v_add_f32_e32 v2, v2, v129
	v_lshlrev_b32_e32 v130, 16, v130
	v_add_f32_e32 v2, v2, v130
	v_lshlrev_b32_e32 v131, 16, v131
	v_add_f32_e32 v2, v2, v131
	v_lshlrev_b32_e32 v132, 16, v132
	v_add_f32_e32 v2, v2, v132
	v_lshlrev_b32_e32 v133, 16, v133
	v_add_f32_e32 v2, v2, v133
	v_lshlrev_b32_e32 v134, 16, v134
	v_add_f32_e32 v2, v2, v134
	v_lshlrev_b32_e32 v135, 16, v135
	v_add_f32_e32 v2, v2, v135
	v_lshlrev_b32_e32 v136, 16, v136
	v_add_f32_e32 v2, v2, v136
	v_lshlrev_b32_e32 v137, 16, v137
	v_add_f32_e32 v2, v2, v137
	v_lshlrev_b32_e32 v138, 16, v138
	v_add_f32_e32 v2, v2, v138
	v_lshlrev_b32_e32 v139, 16, v139
	v_add_f32_e32 v2, v2, v139
	v_lshlrev_b32_e32 v166, 16, v166
	v_add_f32_e32 v2, v2, v166
	v_lshlrev_b32_e32 v167, 16, v167
	v_add_f32_e32 v2, v2, v167
	s_waitcnt lgkmcnt(15)
	v_lshlrev_b32_e32 v168, 16, v168
	v_add_f32_e32 v2, v2, v168
	s_waitcnt lgkmcnt(14)
	v_lshlrev_b32_e32 v169, 16, v169
	v_add_f32_e32 v2, v2, v169
	s_waitcnt lgkmcnt(13)
	v_lshlrev_b32_e32 v170, 16, v170
	v_add_f32_e32 v2, v2, v170
	s_waitcnt lgkmcnt(12)
	v_lshlrev_b32_e32 v171, 16, v171
	v_add_f32_e32 v2, v2, v171
	s_waitcnt lgkmcnt(11)
	v_lshlrev_b32_e32 v172, 16, v172
	v_add_f32_e32 v2, v2, v172
	s_waitcnt lgkmcnt(10)
	v_lshlrev_b32_e32 v173, 16, v173
	v_add_f32_e32 v2, v2, v173
	s_waitcnt lgkmcnt(9)
	v_lshlrev_b32_e32 v174, 16, v174
	v_add_f32_e32 v2, v2, v174
	s_waitcnt lgkmcnt(8)
	v_lshlrev_b32_e32 v175, 16, v175
	v_add_f32_e32 v2, v2, v175
	s_waitcnt lgkmcnt(7)
	v_lshlrev_b32_e32 v176, 16, v176
	v_add_f32_e32 v2, v2, v176
	s_waitcnt lgkmcnt(6)
	v_lshlrev_b32_e32 v177, 16, v177
	v_add_f32_e32 v2, v2, v177
	s_waitcnt lgkmcnt(5)
	v_lshlrev_b32_e32 v178, 16, v178
	v_add_f32_e32 v2, v2, v178
	s_waitcnt lgkmcnt(4)
	v_lshlrev_b32_e32 v179, 16, v179
	v_add_f32_e32 v2, v2, v179
	s_waitcnt lgkmcnt(3)
	v_lshlrev_b32_e32 v180, 16, v180
	v_add_f32_e32 v2, v2, v180
	s_waitcnt lgkmcnt(2)
	v_lshlrev_b32_e32 v181, 16, v181
	v_add_f32_e32 v2, v2, v181
	s_waitcnt lgkmcnt(1)
	v_lshlrev_b32_e32 v182, 16, v182
	v_add_f32_e32 v2, v2, v182
	s_waitcnt lgkmcnt(0)
	v_lshlrev_b32_e32 v233, 16, v233
	v_add_f32_e32 v2, v2, v233
	v_pk_mul_f32 v[18:19], v[18:19], v[110:111]
	v_pk_mul_f32 v[16:17], v[16:17], v[108:109]
	v_pk_mul_f32 v[14:15], v[14:15], v[106:107]
	v_pk_mul_f32 v[12:13], v[12:13], v[104:105]
	v_pk_mul_f32 v[10:11], v[10:11], v[102:103]
	v_pk_mul_f32 v[8:9], v[8:9], v[100:101]
	v_pk_mul_f32 v[6:7], v[6:7], v[98:99]
	v_pk_mul_f32 v[4:5], v[4:5], v[96:97]
	v_pk_mul_f32 v[50:51], v[50:51], v[110:111]
	v_pk_mul_f32 v[48:49], v[48:49], v[108:109]
	v_pk_mul_f32 v[46:47], v[46:47], v[106:107]
	v_pk_mul_f32 v[44:45], v[44:45], v[104:105]
	v_pk_mul_f32 v[42:43], v[42:43], v[102:103]
	v_pk_mul_f32 v[40:41], v[40:41], v[100:101]
	v_pk_mul_f32 v[38:39], v[38:39], v[98:99]
	v_pk_mul_f32 v[36:37], v[36:37], v[96:97]
	v_mfma_f32_32x32x16_bf16 v[4:19], v[76:79], v[68:71], v[4:19]
	v_fmac_f32_e32 v2, v226, v96
	s_add_i32 s50, s50, 1
	s_cmp_eq_u32 s50, 4
	v_mov_b32_e32 v226, v2
	ds_write_b32 v149, v2 offset:16896
	v_mfma_f32_32x32x16_bf16 v[36:51], v[88:91], v[68:71], v[36:51]
	v_mfma_f32_32x32x16_bf16 v[4:19], v[80:83], v[72:75], v[4:19]
	v_mfma_f32_32x32x16_bf16 v[36:51], v[92:95], v[72:75], v[36:51]
	v_mfma_f32_32x32x16_bf16 v[52:67], v[92:95], v[84:87], v[52:67]
	s_cbranch_scc0 .LBB0_787
	s_mov_b64 s[92:93], 0x80
	s_mov_b32 s48, s2

; #define LAS __attribute__((address_space(3)))
; template <bool OUT>
; __device__ __forceinline__ void mlstm_item(const bf16* u, bf16* y, float* scratch, const float* convw, const float* ib, const float* fbias, const float* normw, LAS unsigned char* wl, int bh, int c, int lane) {
;     const int b = bh / 6, h = bh % 6, r = lane & 31, hi = lane >> 5;
;     const bf16* ub = u + (size_t)b * S * NU;
;     LAS float* cw = (LAS float*)(wl + ML_CW); LAS float* eb = (LAS float*)(wl + ML_EB); LAS float* nl = (LAS float*)(wl + ML_NL); LAS float* nwl = (LAS float*)(wl + ML_NW);
; __global__ void __launch_bounds__(512, 2) mega_fwd(Args a) {
;     ...
;                     if (it >= 48) { __builtin_amdgcn_s_setprio(3); mlstm_item<false>(ub, yb, mscr, prm + 512, prm + 8, prm + 16, prm + 64, L + wave * ML_WSTRIDE, xcd + 8 * ((it - 48) / 15), (it - 48) % 15, lane); __builtin_amdgcn_s_setprio(0); }
.LBB0_801:
	s_andn2_b64 vcc, exec, s[0:1]
	s_mov_b64 s[0:1], 0
	s_cbranch_vccnz .LBB0_815
	s_add_i32 s98, s98, 0xffd0
	s_and_b32 s0, s98, 0xff
	s_mulk_i32 s0, 0x89
	s_bfe_u32 s3, s0, 0x5000b
	s_lshr_b32 s0, s0, 8
	s_and_b32 s0, s0, 0xf8
	s_or_b32 s2, s69, s0
	s_and_b32 s0, s2, 0xff
	s_mulk_i32 s0, 0xab
	s_lshr_b32 s51, s0, 10
	s_mul_i32 s0, s51, 6
	s_sub_i32 s0, s2, s0
	s_and_b32 s50, s0, 0xff
	s_lshl_b32 s33, s50, 6
	s_add_i32 s52, s33, 0x140
	s_mov_b64 s[0:1], 0
	v_mov_b32_e32 v1, v220
	v_mov_b32_e32 v4, v202

; __global__ void __launch_bounds__(512, 2) mega_fwd(Args a) {
;     ...
;                     if (it >= 48) { __builtin_amdgcn_s_setprio(3); mlstm_item<false>(ub, yb, mscr, prm + 512, prm + 8, prm + 16, prm + 64, L + wave * ML_WSTRIDE, xcd + 8 * ((it - 48) / 15), (it - 48) % 15, lane); __builtin_amdgcn_s_setprio(0); }
;                     else fox_cumsum_item(ub, prm, fcl, ftot, (xcd + 8 * (it >> 3)) * 8 + (it & 7), lane);
;                     asm volatile("s_waitcnt vmcnt(0)" ::: "memory");
;                     if (lane == 0) atomicAdd(done + (it >= 48 ? 8 : 0), 1u);
.LBB0_814:
	s_or_b64 exec, exec, s[50:51]
	s_mov_b64 s[0:1], 8
